# OUTPROJ hooks/epilogue and UP epilogue: removed 512 sNaN-canonicalising v_max (hazard re-padded), on top of slab+rwkv loader+ssd batch+p0wait
# speedup vs baseline: 1.0064x; 1.0064x over previous
; __device__ __forceinline__ float bflo(unsigned u) { return __uint_as_float(u << 16); }
; __device__ __forceinline__ float bfhi(unsigned u) { return __uint_as_float(u & 0xffff0000u); }
; __device__ __forceinline__ float bflo(unsigned u) { return __uint_as_float(u << 16); }
; __device__ __forceinline__ float bfhi(unsigned u) { return __uint_as_float(u & 0xffff0000u); }
;     __device__ __forceinline__ void khook(f32x4 (&acc)[2][2][4][2], const Unit& u, int t, int wr, int wc, int fr, int fq) const {
;         const int i = (t == 8) ? 0 : (t == 20 ? 1 : 2);
;         int row0 = u.pm * BM + wr * 64 + fr; const int col0 = u.pn * BM + wc * 32 + 8 * fq + i * 2048;
;         asm volatile("" : "+v"(row0));
; #pragma unroll
;         for (int ai = 0; ai < 2; ++ai) {
;             u32x4 gv[4][2], hv[4][2];
; #pragma unroll
;             for (int m = 0; m < 4; ++m) { const bf16_t* gp = G + (size_t)(row0 + ai * HALF + m * 16) * ldg + col0;
; #pragma unroll
;                 for (int bj = 0; bj < 2; ++bj) { gv[m][bj] = *(const u32x4*)(gp + bj * HALF); hv[m][bj] = *(const u32x4*)(gp + bj * HALF + 2048); } }
;             asm volatile("" ::: "memory");
; #pragma unroll
;             for (int m = 0; m < 4; ++m)
; #pragma unroll
;                 for (int bj = 0; bj < 2; ++bj) { const u32x4 g = gv[m][bj], h = hv[m][bj];
;                     const unsigned gw[4] = {g.x, g.y, g.z, g.w}, hw[4] = {h.x, h.y, h.z, h.w};
; #pragma unroll
;                     for (int e2 = 0; e2 < 4; ++e2) { const float r0 = fmaxf(bflo(gw[e2]), 1e-6f) * __builtin_amdgcn_rcpf(fmaxf(bflo(hw[e2]), 1e-6f)), r1 = fmaxf(bfhi(gw[e2]), 1e-6f) * __builtin_amdgcn_rcpf(fmaxf(bfhi(hw[e2]), 1e-6f));
;                         acc[ai][bj][m][e2 >> 1][(e2 & 1) * 2] *= r0; acc[ai][bj][m][e2 >> 1][(e2 & 1) * 2 + 1] *= r1; } }
.LBB0_1393:
	s_cmpk_eq_i32 s34, 0xa00
	s_movk_i32 s7, 0x1000
	s_cselect_b32 s4, 0x800, s7
	s_cmpk_lg_i32 s34, 0x400
	s_cselect_b32 s4, s4, 0
	v_add_u32_e32 v132, s4, v208
	v_ashrrev_i32_e32 v133, 31, v132
	v_mov_b32_e32 v0, v2
	v_lshl_add_u64 v[214:215], v[132:133], 1, s[2:3]
	s_movk_i32 s6, 0x6c00
	s_nop 0
	v_mad_i64_i32 v[132:133], s[4:5], v0, s6, v[214:215]
	global_load_dwordx4 v[192:195], v[132:133], off
	v_add_co_u32_e32 v134, vcc, 0x1000, v132
	v_add_u32_e32 v3, 16, v0
	s_nop 0
	v_addc_co_u32_e32 v135, vcc, 0, v133, vcc
	global_load_dwordx4 v[188:191], v[134:135], off
	global_load_dwordx4 v[184:187], v[132:133], off offset:256
	global_load_dwordx4 v[180:183], v[134:135], off offset:256
	v_mad_i64_i32 v[132:133], s[4:5], v3, s6, v[214:215]
	v_add_co_u32_e32 v134, vcc, 0x1000, v132
	v_add_u32_e32 v3, 32, v0
	s_nop 0
	v_addc_co_u32_e32 v135, vcc, 0, v133, vcc
	global_load_dwordx4 v[176:179], v[132:133], off
	global_load_dwordx4 v[172:175], v[134:135], off
	global_load_dwordx4 v[168:171], v[132:133], off offset:256
	global_load_dwordx4 v[164:167], v[134:135], off offset:256
	v_mad_i64_i32 v[132:133], s[4:5], v3, s6, v[214:215]
	v_add_co_u32_e32 v134, vcc, 0x1000, v132
	v_add_u32_e32 v3, 48, v0
	s_nop 0
	v_addc_co_u32_e32 v135, vcc, 0, v133, vcc
	global_load_dwordx4 v[160:163], v[132:133], off
	global_load_dwordx4 v[156:159], v[134:135], off
	global_load_dwordx4 v[152:155], v[132:133], off offset:256
	global_load_dwordx4 v[148:151], v[134:135], off offset:256
	v_mad_i64_i32 v[132:133], s[4:5], v3, s6, v[214:215]
	global_load_dwordx4 v[144:147], v[132:133], off
	v_add_co_u32_e32 v136, vcc, 0x1000, v132
	s_waitcnt vmcnt(0)
	v_lshlrev_b32_e32 v3, 16, v192
	v_max_f32_e32 v220, 0x358637bd, v3
	v_addc_co_u32_e32 v137, vcc, 0, v133, vcc
	v_lshlrev_b32_e32 v3, 16, v188
	v_max_f32_e32 v3, 0x358637bd, v3
	v_rcp_f32_e32 v222, v3
	v_and_b32_e32 v3, 0xffff0000, v192
	v_max_f32_e32 v221, 0x358637bd, v3
	v_and_b32_e32 v3, 0xffff0000, v188
	v_max_f32_e32 v3, 0x358637bd, v3
	v_rcp_f32_e32 v223, v3
	v_lshlrev_b32_e32 v3, 16, v193
	v_max_f32_e32 v192, 0x358637bd, v3
	v_lshlrev_b32_e32 v3, 16, v189
	v_max_f32_e32 v3, 0x358637bd, v3
	v_rcp_f32_e32 v188, v3
	v_and_b32_e32 v3, 0xffff0000, v193
	v_max_f32_e32 v193, 0x358637bd, v3
	v_and_b32_e32 v3, 0xffff0000, v189
	v_max_f32_e32 v3, 0x358637bd, v3
	v_rcp_f32_e32 v189, v3
	v_lshlrev_b32_e32 v3, 16, v194
	global_load_dwordx4 v[140:143], v[136:137], off
	s_nop 0
	global_load_dwordx4 v[132:135], v[132:133], off offset:256
	s_nop 0
	global_load_dwordx4 v[136:139], v[136:137], off offset:256
	v_pk_mul_f32 v[188:189], v[192:193], v[188:189]
	v_pk_mul_f32 v[220:221], v[220:221], v[222:223]
	v_pk_mul_f32 v[130:131], v[130:131], v[188:189]
	v_max_f32_e32 v188, 0x358637bd, v3
	v_lshlrev_b32_e32 v3, 16, v190
	v_max_f32_e32 v3, 0x358637bd, v3
	v_rcp_f32_e32 v192, v3
	v_and_b32_e32 v3, 0xffff0000, v194
	v_max_f32_e32 v189, 0x358637bd, v3
	v_and_b32_e32 v3, 0xffff0000, v190
	v_max_f32_e32 v3, 0x358637bd, v3
	v_rcp_f32_e32 v193, v3
	v_lshlrev_b32_e32 v3, 16, v195
	v_max_f32_e32 v194, 0x358637bd, v3
	v_lshlrev_b32_e32 v3, 16, v191
	v_max_f32_e32 v3, 0x358637bd, v3
	v_rcp_f32_e32 v190, v3
	v_and_b32_e32 v3, 0xffff0000, v195
	v_max_f32_e32 v195, 0x358637bd, v3
	v_and_b32_e32 v3, 0xffff0000, v191
	v_max_f32_e32 v3, 0x358637bd, v3
	v_rcp_f32_e32 v191, v3
	v_lshlrev_b32_e32 v3, 16, v184
	v_pk_mul_f32 v[188:189], v[188:189], v[192:193]
	v_pk_mul_f32 v[124:125], v[124:125], v[188:189]
	v_max_f32_e32 v188, 0x358637bd, v3
	v_lshlrev_b32_e32 v3, 16, v180
	v_pk_mul_f32 v[190:191], v[194:195], v[190:191]
	v_max_f32_e32 v3, 0x358637bd, v3
	v_pk_mul_f32 v[126:127], v[126:127], v[190:191]
	v_rcp_f32_e32 v190, v3
	v_and_b32_e32 v3, 0xffff0000, v184
	v_max_f32_e32 v189, 0x358637bd, v3
	v_and_b32_e32 v3, 0xffff0000, v180
	v_max_f32_e32 v3, 0x358637bd, v3
	v_rcp_f32_e32 v191, v3
	v_lshlrev_b32_e32 v3, 16, v185
	v_max_f32_e32 v184, 0x358637bd, v3
	v_lshlrev_b32_e32 v3, 16, v181
	v_max_f32_e32 v3, 0x358637bd, v3
	v_rcp_f32_e32 v180, v3
	v_and_b32_e32 v3, 0xffff0000, v185
	v_max_f32_e32 v185, 0x358637bd, v3
	v_and_b32_e32 v3, 0xffff0000, v181
	v_max_f32_e32 v3, 0x358637bd, v3
	v_rcp_f32_e32 v181, v3
	v_lshlrev_b32_e32 v3, 16, v186
	v_pk_mul_f32 v[188:189], v[188:189], v[190:191]
	v_pk_mul_f32 v[180:181], v[184:185], v[180:181]
	v_pk_mul_f32 v[96:97], v[96:97], v[188:189]
	v_pk_mul_f32 v[98:99], v[98:99], v[180:181]
	v_max_f32_e32 v180, 0x358637bd, v3
	v_lshlrev_b32_e32 v3, 16, v182
	v_max_f32_e32 v3, 0x358637bd, v3
	v_rcp_f32_e32 v184, v3
	v_and_b32_e32 v3, 0xffff0000, v186
	v_max_f32_e32 v181, 0x358637bd, v3
	v_and_b32_e32 v3, 0xffff0000, v182
	v_max_f32_e32 v3, 0x358637bd, v3
	v_rcp_f32_e32 v185, v3
	v_lshlrev_b32_e32 v3, 16, v187
	v_max_f32_e32 v186, 0x358637bd, v3
	v_lshlrev_b32_e32 v3, 16, v183
	v_max_f32_e32 v3, 0x358637bd, v3
	v_rcp_f32_e32 v182, v3
	v_and_b32_e32 v3, 0xffff0000, v187
	v_max_f32_e32 v187, 0x358637bd, v3
	v_and_b32_e32 v3, 0xffff0000, v183
	v_max_f32_e32 v3, 0x358637bd, v3
	v_rcp_f32_e32 v183, v3
	v_lshlrev_b32_e32 v3, 16, v176
	v_pk_mul_f32 v[180:181], v[180:181], v[184:185]
	v_pk_mul_f32 v[92:93], v[92:93], v[180:181]
	v_max_f32_e32 v180, 0x358637bd, v3
	v_lshlrev_b32_e32 v3, 16, v172
	v_pk_mul_f32 v[182:183], v[186:187], v[182:183]
	v_max_f32_e32 v3, 0x358637bd, v3
	v_pk_mul_f32 v[94:95], v[94:95], v[182:183]
	v_rcp_f32_e32 v182, v3
	v_and_b32_e32 v3, 0xffff0000, v176
	v_max_f32_e32 v181, 0x358637bd, v3
	v_and_b32_e32 v3, 0xffff0000, v172
	v_max_f32_e32 v3, 0x358637bd, v3
	v_rcp_f32_e32 v183, v3
	v_lshlrev_b32_e32 v3, 16, v177
	v_max_f32_e32 v176, 0x358637bd, v3
	v_lshlrev_b32_e32 v3, 16, v173
	v_max_f32_e32 v3, 0x358637bd, v3
; __device__ __forceinline__ float bflo(unsigned u) { return __uint_as_float(u << 16); }
; __device__ __forceinline__ float bfhi(unsigned u) { return __uint_as_float(u & 0xffff0000u); }
; __device__ __forceinline__ float bflo(unsigned u) { return __uint_as_float(u << 16); }
; __device__ __forceinline__ float bfhi(unsigned u) { return __uint_as_float(u & 0xffff0000u); }
;     __device__ __forceinline__ void khook(f32x4 (&acc)[2][2][4][2], const Unit& u, int t, int wr, int wc, int fr, int fq) const {
;     ...
;         for (int ai = 0; ai < 2; ++ai) {
;             u32x4 gv[4][2], hv[4][2];
; #pragma unroll
;             for (int m = 0; m < 4; ++m) { const bf16_t* gp = G + (size_t)(row0 + ai * HALF + m * 16) * ldg + col0;
; #pragma unroll
;                 for (int bj = 0; bj < 2; ++bj) { gv[m][bj] = *(const u32x4*)(gp + bj * HALF); hv[m][bj] = *(const u32x4*)(gp + bj * HALF + 2048); } }
;             asm volatile("" ::: "memory");
; #pragma unroll
;             for (int m = 0; m < 4; ++m)
; #pragma unroll
;                 for (int bj = 0; bj < 2; ++bj) { const u32x4 g = gv[m][bj], h = hv[m][bj];
;                     const unsigned gw[4] = {g.x, g.y, g.z, g.w}, hw[4] = {h.x, h.y, h.z, h.w};
; #pragma unroll
;                     for (int e2 = 0; e2 < 4; ++e2) { const float r0 = fmaxf(bflo(gw[e2]), 1e-6f) * __builtin_amdgcn_rcpf(fmaxf(bflo(hw[e2]), 1e-6f)), r1 = fmaxf(bfhi(gw[e2]), 1e-6f) * __builtin_amdgcn_rcpf(fmaxf(bfhi(hw[e2]), 1e-6f));
;                         acc[ai][bj][m][e2 >> 1][(e2 & 1) * 2] *= r0; acc[ai][bj][m][e2 >> 1][(e2 & 1) * 2 + 1] *= r1; } }
	v_rcp_f32_e32 v172, v3
	v_and_b32_e32 v3, 0xffff0000, v177
	v_max_f32_e32 v177, 0x358637bd, v3
	v_and_b32_e32 v3, 0xffff0000, v173
	v_max_f32_e32 v3, 0x358637bd, v3
	v_rcp_f32_e32 v173, v3
	v_lshlrev_b32_e32 v3, 16, v178
	v_pk_mul_f32 v[180:181], v[180:181], v[182:183]
	v_pk_mul_f32 v[172:173], v[176:177], v[172:173]
	v_pk_mul_f32 v[120:121], v[120:121], v[180:181]
	v_pk_mul_f32 v[122:123], v[122:123], v[172:173]
	v_max_f32_e32 v172, 0x358637bd, v3
	v_lshlrev_b32_e32 v3, 16, v174
	v_max_f32_e32 v3, 0x358637bd, v3
	v_rcp_f32_e32 v176, v3
	v_and_b32_e32 v3, 0xffff0000, v178
	v_max_f32_e32 v173, 0x358637bd, v3
	v_and_b32_e32 v3, 0xffff0000, v174
	v_max_f32_e32 v3, 0x358637bd, v3
	v_rcp_f32_e32 v177, v3
	v_lshlrev_b32_e32 v3, 16, v179
	v_max_f32_e32 v178, 0x358637bd, v3
	v_lshlrev_b32_e32 v3, 16, v175
	v_max_f32_e32 v3, 0x358637bd, v3
	v_rcp_f32_e32 v174, v3
	v_and_b32_e32 v3, 0xffff0000, v179
	v_max_f32_e32 v179, 0x358637bd, v3
	v_and_b32_e32 v3, 0xffff0000, v175
	v_max_f32_e32 v3, 0x358637bd, v3
	v_rcp_f32_e32 v175, v3
	v_lshlrev_b32_e32 v3, 16, v168
	v_pk_mul_f32 v[172:173], v[172:173], v[176:177]
	v_pk_mul_f32 v[116:117], v[116:117], v[172:173]
	v_max_f32_e32 v172, 0x358637bd, v3
	v_lshlrev_b32_e32 v3, 16, v164
	v_pk_mul_f32 v[174:175], v[178:179], v[174:175]
	v_max_f32_e32 v3, 0x358637bd, v3
	v_pk_mul_f32 v[118:119], v[118:119], v[174:175]
	v_rcp_f32_e32 v174, v3
	v_and_b32_e32 v3, 0xffff0000, v168
	v_max_f32_e32 v173, 0x358637bd, v3
	v_and_b32_e32 v3, 0xffff0000, v164
	v_max_f32_e32 v3, 0x358637bd, v3
	v_rcp_f32_e32 v175, v3
	v_lshlrev_b32_e32 v3, 16, v169
	v_max_f32_e32 v168, 0x358637bd, v3
	v_lshlrev_b32_e32 v3, 16, v165
	v_max_f32_e32 v3, 0x358637bd, v3
	v_rcp_f32_e32 v164, v3
	v_and_b32_e32 v3, 0xffff0000, v169
	v_max_f32_e32 v169, 0x358637bd, v3
	v_and_b32_e32 v3, 0xffff0000, v165
	v_max_f32_e32 v3, 0x358637bd, v3
	v_rcp_f32_e32 v165, v3
	v_lshlrev_b32_e32 v3, 16, v170
	v_pk_mul_f32 v[172:173], v[172:173], v[174:175]
	v_pk_mul_f32 v[164:165], v[168:169], v[164:165]
	v_pk_mul_f32 v[88:89], v[88:89], v[172:173]
	v_pk_mul_f32 v[90:91], v[90:91], v[164:165]
	v_max_f32_e32 v164, 0x358637bd, v3
	v_lshlrev_b32_e32 v3, 16, v166
	v_max_f32_e32 v3, 0x358637bd, v3
	v_rcp_f32_e32 v168, v3
	v_and_b32_e32 v3, 0xffff0000, v170
	v_max_f32_e32 v165, 0x358637bd, v3
	v_and_b32_e32 v3, 0xffff0000, v166
	v_max_f32_e32 v3, 0x358637bd, v3
	v_rcp_f32_e32 v169, v3
	v_lshlrev_b32_e32 v3, 16, v171
	v_max_f32_e32 v170, 0x358637bd, v3
	v_lshlrev_b32_e32 v3, 16, v167
	v_max_f32_e32 v3, 0x358637bd, v3
	v_rcp_f32_e32 v166, v3
	v_and_b32_e32 v3, 0xffff0000, v171
	v_max_f32_e32 v171, 0x358637bd, v3
	v_and_b32_e32 v3, 0xffff0000, v167
	v_max_f32_e32 v3, 0x358637bd, v3
	v_rcp_f32_e32 v167, v3
	v_lshlrev_b32_e32 v3, 16, v160
	v_pk_mul_f32 v[164:165], v[164:165], v[168:169]
	v_pk_mul_f32 v[84:85], v[84:85], v[164:165]
	v_max_f32_e32 v164, 0x358637bd, v3
	v_lshlrev_b32_e32 v3, 16, v156
	v_pk_mul_f32 v[166:167], v[170:171], v[166:167]
	v_max_f32_e32 v3, 0x358637bd, v3
	v_pk_mul_f32 v[86:87], v[86:87], v[166:167]
	v_rcp_f32_e32 v166, v3
	v_and_b32_e32 v3, 0xffff0000, v160
	v_max_f32_e32 v165, 0x358637bd, v3
	v_and_b32_e32 v3, 0xffff0000, v156
	v_max_f32_e32 v3, 0x358637bd, v3
	v_rcp_f32_e32 v167, v3
	v_lshlrev_b32_e32 v3, 16, v161
	v_max_f32_e32 v160, 0x358637bd, v3
	v_lshlrev_b32_e32 v3, 16, v157
	v_max_f32_e32 v3, 0x358637bd, v3
	v_rcp_f32_e32 v156, v3
	v_and_b32_e32 v3, 0xffff0000, v161
	v_max_f32_e32 v161, 0x358637bd, v3
	v_and_b32_e32 v3, 0xffff0000, v157
	v_max_f32_e32 v3, 0x358637bd, v3
	v_rcp_f32_e32 v157, v3
	v_lshlrev_b32_e32 v3, 16, v162
	v_pk_mul_f32 v[164:165], v[164:165], v[166:167]
	v_pk_mul_f32 v[156:157], v[160:161], v[156:157]
	v_pk_mul_f32 v[112:113], v[112:113], v[164:165]
	v_pk_mul_f32 v[114:115], v[114:115], v[156:157]
	v_max_f32_e32 v156, 0x358637bd, v3
	v_lshlrev_b32_e32 v3, 16, v158
	v_max_f32_e32 v3, 0x358637bd, v3
	v_rcp_f32_e32 v160, v3
	v_and_b32_e32 v3, 0xffff0000, v162
	v_max_f32_e32 v157, 0x358637bd, v3
	v_and_b32_e32 v3, 0xffff0000, v158
	v_max_f32_e32 v3, 0x358637bd, v3
	v_rcp_f32_e32 v161, v3
	v_lshlrev_b32_e32 v3, 16, v163
	v_max_f32_e32 v162, 0x358637bd, v3
	v_lshlrev_b32_e32 v3, 16, v159
	v_max_f32_e32 v3, 0x358637bd, v3
	v_rcp_f32_e32 v158, v3
	v_and_b32_e32 v3, 0xffff0000, v163
	v_max_f32_e32 v163, 0x358637bd, v3
	v_and_b32_e32 v3, 0xffff0000, v159
	v_max_f32_e32 v3, 0x358637bd, v3
	v_rcp_f32_e32 v159, v3
	v_lshlrev_b32_e32 v3, 16, v152
	v_pk_mul_f32 v[156:157], v[156:157], v[160:161]
	v_pk_mul_f32 v[108:109], v[108:109], v[156:157]
	v_max_f32_e32 v156, 0x358637bd, v3
	v_lshlrev_b32_e32 v3, 16, v148
	v_pk_mul_f32 v[158:159], v[162:163], v[158:159]
	v_max_f32_e32 v3, 0x358637bd, v3
	v_pk_mul_f32 v[110:111], v[110:111], v[158:159]
	v_rcp_f32_e32 v158, v3
	v_and_b32_e32 v3, 0xffff0000, v152
	v_max_f32_e32 v157, 0x358637bd, v3
	v_and_b32_e32 v3, 0xffff0000, v148
	v_max_f32_e32 v3, 0x358637bd, v3
	v_rcp_f32_e32 v159, v3
	v_lshlrev_b32_e32 v3, 16, v153
	v_max_f32_e32 v152, 0x358637bd, v3
	v_lshlrev_b32_e32 v3, 16, v149
	v_max_f32_e32 v3, 0x358637bd, v3
	v_rcp_f32_e32 v148, v3
	v_and_b32_e32 v3, 0xffff0000, v153
	v_max_f32_e32 v153, 0x358637bd, v3
	v_and_b32_e32 v3, 0xffff0000, v149
	v_max_f32_e32 v3, 0x358637bd, v3
	v_rcp_f32_e32 v149, v3
	v_lshlrev_b32_e32 v3, 16, v154
	v_pk_mul_f32 v[156:157], v[156:157], v[158:159]
	v_pk_mul_f32 v[148:149], v[152:153], v[148:149]
	v_pk_mul_f32 v[80:81], v[80:81], v[156:157]
	v_pk_mul_f32 v[82:83], v[82:83], v[148:149]
	v_max_f32_e32 v148, 0x358637bd, v3
	v_lshlrev_b32_e32 v3, 16, v150
	v_max_f32_e32 v3, 0x358637bd, v3
	v_rcp_f32_e32 v152, v3
	v_and_b32_e32 v3, 0xffff0000, v154
	v_max_f32_e32 v149, 0x358637bd, v3
	v_and_b32_e32 v3, 0xffff0000, v150
	v_max_f32_e32 v3, 0x358637bd, v3
	v_rcp_f32_e32 v153, v3
	v_lshlrev_b32_e32 v3, 16, v155
	v_max_f32_e32 v154, 0x358637bd, v3
	v_lshlrev_b32_e32 v3, 16, v151
	v_max_f32_e32 v3, 0x358637bd, v3
	v_rcp_f32_e32 v150, v3
	v_and_b32_e32 v3, 0xffff0000, v155
	v_max_f32_e32 v155, 0x358637bd, v3
	v_and_b32_e32 v3, 0xffff0000, v151
	v_max_f32_e32 v3, 0x358637bd, v3
	v_rcp_f32_e32 v151, v3
	v_lshlrev_b32_e32 v3, 16, v144
	v_pk_mul_f32 v[148:149], v[148:149], v[152:153]
	v_pk_mul_f32 v[76:77], v[76:77], v[148:149]
	v_max_f32_e32 v148, 0x358637bd, v3
	s_waitcnt vmcnt(0)
; __device__ __forceinline__ float bflo(unsigned u) { return __uint_as_float(u << 16); }
; __device__ __forceinline__ float bfhi(unsigned u) { return __uint_as_float(u & 0xffff0000u); }
; __device__ __forceinline__ float bflo(unsigned u) { return __uint_as_float(u << 16); }
; __device__ __forceinline__ float bfhi(unsigned u) { return __uint_as_float(u & 0xffff0000u); }
;     __device__ __forceinline__ void khook(f32x4 (&acc)[2][2][4][2], const Unit& u, int t, int wr, int wc, int fr, int fq) const {
;     ...
;         for (int ai = 0; ai < 2; ++ai) {
;             u32x4 gv[4][2], hv[4][2];
; #pragma unroll
;             for (int m = 0; m < 4; ++m) { const bf16_t* gp = G + (size_t)(row0 + ai * HALF + m * 16) * ldg + col0;
; #pragma unroll
;                 for (int bj = 0; bj < 2; ++bj) { gv[m][bj] = *(const u32x4*)(gp + bj * HALF); hv[m][bj] = *(const u32x4*)(gp + bj * HALF + 2048); } }
;             asm volatile("" ::: "memory");
; #pragma unroll
;             for (int m = 0; m < 4; ++m)
; #pragma unroll
;                 for (int bj = 0; bj < 2; ++bj) { const u32x4 g = gv[m][bj], h = hv[m][bj];
;                     const unsigned gw[4] = {g.x, g.y, g.z, g.w}, hw[4] = {h.x, h.y, h.z, h.w};
; #pragma unroll
;                     for (int e2 = 0; e2 < 4; ++e2) { const float r0 = fmaxf(bflo(gw[e2]), 1e-6f) * __builtin_amdgcn_rcpf(fmaxf(bflo(hw[e2]), 1e-6f)), r1 = fmaxf(bfhi(gw[e2]), 1e-6f) * __builtin_amdgcn_rcpf(fmaxf(bfhi(hw[e2]), 1e-6f));
;                         acc[ai][bj][m][e2 >> 1][(e2 & 1) * 2] *= r0; acc[ai][bj][m][e2 >> 1][(e2 & 1) * 2 + 1] *= r1; } }
	v_lshlrev_b32_e32 v3, 16, v140
	v_pk_mul_f32 v[150:151], v[154:155], v[150:151]
	v_max_f32_e32 v3, 0x358637bd, v3
	v_pk_mul_f32 v[78:79], v[78:79], v[150:151]
	v_rcp_f32_e32 v150, v3
	v_and_b32_e32 v3, 0xffff0000, v144
	v_max_f32_e32 v149, 0x358637bd, v3
	v_and_b32_e32 v3, 0xffff0000, v140
	v_max_f32_e32 v3, 0x358637bd, v3
	v_rcp_f32_e32 v151, v3
	v_lshlrev_b32_e32 v3, 16, v145
	v_max_f32_e32 v144, 0x358637bd, v3
	v_lshlrev_b32_e32 v3, 16, v141
	v_max_f32_e32 v3, 0x358637bd, v3
	v_rcp_f32_e32 v140, v3
	v_and_b32_e32 v3, 0xffff0000, v145
	v_max_f32_e32 v145, 0x358637bd, v3
	v_and_b32_e32 v3, 0xffff0000, v141
	v_max_f32_e32 v3, 0x358637bd, v3
	v_rcp_f32_e32 v141, v3
	v_lshlrev_b32_e32 v3, 16, v146
	v_pk_mul_f32 v[148:149], v[148:149], v[150:151]
	v_pk_mul_f32 v[140:141], v[144:145], v[140:141]
	v_pk_mul_f32 v[104:105], v[104:105], v[148:149]
	v_pk_mul_f32 v[106:107], v[106:107], v[140:141]
	v_max_f32_e32 v140, 0x358637bd, v3
	v_lshlrev_b32_e32 v3, 16, v142
	v_max_f32_e32 v3, 0x358637bd, v3
	v_rcp_f32_e32 v144, v3
	v_and_b32_e32 v3, 0xffff0000, v146
	v_max_f32_e32 v141, 0x358637bd, v3
	v_and_b32_e32 v3, 0xffff0000, v142
	v_max_f32_e32 v3, 0x358637bd, v3
	v_rcp_f32_e32 v145, v3
	v_lshlrev_b32_e32 v3, 16, v147
	v_max_f32_e32 v146, 0x358637bd, v3
	v_lshlrev_b32_e32 v3, 16, v143
	v_max_f32_e32 v3, 0x358637bd, v3
	v_rcp_f32_e32 v142, v3
	v_and_b32_e32 v3, 0xffff0000, v147
	v_max_f32_e32 v147, 0x358637bd, v3
	v_and_b32_e32 v3, 0xffff0000, v143
	v_max_f32_e32 v3, 0x358637bd, v3
	v_rcp_f32_e32 v143, v3
	v_lshlrev_b32_e32 v3, 16, v132
	v_pk_mul_f32 v[140:141], v[140:141], v[144:145]
	v_pk_mul_f32 v[100:101], v[100:101], v[140:141]
	v_max_f32_e32 v140, 0x358637bd, v3
	v_lshlrev_b32_e32 v3, 16, v136
	v_pk_mul_f32 v[142:143], v[146:147], v[142:143]
	v_max_f32_e32 v3, 0x358637bd, v3
	v_pk_mul_f32 v[102:103], v[102:103], v[142:143]
	v_rcp_f32_e32 v142, v3
	v_and_b32_e32 v3, 0xffff0000, v132
	v_max_f32_e32 v141, 0x358637bd, v3
	v_and_b32_e32 v3, 0xffff0000, v136
	v_max_f32_e32 v3, 0x358637bd, v3
	v_rcp_f32_e32 v143, v3
	v_lshlrev_b32_e32 v3, 16, v133
	v_max_f32_e32 v132, 0x358637bd, v3
	v_lshlrev_b32_e32 v3, 16, v137
	v_max_f32_e32 v3, 0x358637bd, v3
	v_rcp_f32_e32 v136, v3
	v_and_b32_e32 v3, 0xffff0000, v133
	v_max_f32_e32 v133, 0x358637bd, v3
	v_and_b32_e32 v3, 0xffff0000, v137
	v_max_f32_e32 v3, 0x358637bd, v3
	v_rcp_f32_e32 v137, v3
	v_lshlrev_b32_e32 v3, 16, v134
	v_pk_mul_f32 v[128:129], v[128:129], v[220:221]
	v_pk_mul_f32 v[132:133], v[132:133], v[136:137]
	v_pk_mul_f32 v[140:141], v[140:141], v[142:143]
	v_pk_mul_f32 v[74:75], v[74:75], v[132:133]
	v_max_f32_e32 v132, 0x358637bd, v3
	v_lshlrev_b32_e32 v3, 16, v138
	v_max_f32_e32 v3, 0x358637bd, v3
	v_rcp_f32_e32 v136, v3
	v_and_b32_e32 v3, 0xffff0000, v134
	v_max_f32_e32 v133, 0x358637bd, v3
	v_and_b32_e32 v3, 0xffff0000, v138
	v_max_f32_e32 v3, 0x358637bd, v3
	v_rcp_f32_e32 v137, v3
	v_lshlrev_b32_e32 v3, 16, v135
	v_max_f32_e32 v134, 0x358637bd, v3
	v_lshlrev_b32_e32 v3, 16, v139
	v_max_f32_e32 v3, 0x358637bd, v3
	v_rcp_f32_e32 v138, v3
	v_and_b32_e32 v3, 0xffff0000, v135
	v_max_f32_e32 v135, 0x358637bd, v3
	v_and_b32_e32 v3, 0xffff0000, v139
	v_max_f32_e32 v3, 0x358637bd, v3
	v_rcp_f32_e32 v139, v3
	v_pk_mul_f32 v[132:133], v[132:133], v[136:137]
	v_add_u32_e32 v3, 0x80, v0
	v_pk_mul_f32 v[68:69], v[68:69], v[132:133]
	v_mad_i64_i32 v[132:133], s[4:5], v3, s6, v[214:215]
	global_load_dwordx4 v[184:187], v[132:133], off
	v_pk_mul_f32 v[134:135], v[134:135], v[138:139]
	v_add_u32_e32 v3, 0x90, v0
	v_pk_mul_f32 v[70:71], v[70:71], v[134:135]
	v_add_co_u32_e32 v134, vcc, s7, v132
	v_pk_mul_f32 v[72:73], v[72:73], v[140:141]
	s_nop 0
	v_addc_co_u32_e32 v135, vcc, 0, v133, vcc
	global_load_dwordx4 v[180:183], v[134:135], off
	global_load_dwordx4 v[192:195], v[132:133], off offset:256
	global_load_dwordx4 v[188:191], v[134:135], off offset:256
	v_mad_i64_i32 v[132:133], s[4:5], v3, s6, v[214:215]
	v_add_co_u32_e32 v134, vcc, s7, v132
	v_add_u32_e32 v3, 0xa0, v0
	s_nop 0
	v_addc_co_u32_e32 v135, vcc, 0, v133, vcc
	global_load_dwordx4 v[176:179], v[132:133], off
	global_load_dwordx4 v[172:175], v[134:135], off
	global_load_dwordx4 v[168:171], v[132:133], off offset:256
	global_load_dwordx4 v[164:167], v[134:135], off offset:256
	v_mad_i64_i32 v[132:133], s[4:5], v3, s6, v[214:215]
	v_add_co_u32_e32 v134, vcc, s7, v132
	v_add_u32_e32 v0, 0xb0, v0
	s_nop 0
	v_addc_co_u32_e32 v135, vcc, 0, v133, vcc
	global_load_dwordx4 v[160:163], v[132:133], off
	global_load_dwordx4 v[156:159], v[134:135], off
	global_load_dwordx4 v[152:155], v[132:133], off offset:256
	global_load_dwordx4 v[148:151], v[134:135], off offset:256
	v_mad_i64_i32 v[132:133], s[4:5], v0, s6, v[214:215]
	global_load_dwordx4 v[144:147], v[132:133], off
	v_add_co_u32_e32 v134, vcc, s7, v132
	s_waitcnt vmcnt(0)
; __device__ __forceinline__ float bflo(unsigned u) { return __uint_as_float(u << 16); }
; __device__ __forceinline__ float bfhi(unsigned u) { return __uint_as_float(u & 0xffff0000u); }
; __device__ __forceinline__ float bflo(unsigned u) { return __uint_as_float(u << 16); }
; __device__ __forceinline__ float bfhi(unsigned u) { return __uint_as_float(u & 0xffff0000u); }
;     __device__ __forceinline__ void khook(f32x4 (&acc)[2][2][4][2], const Unit& u, int t, int wr, int wc, int fr, int fq) const {
;     ...
;         for (int ai = 0; ai < 2; ++ai) {
;             u32x4 gv[4][2], hv[4][2];
; #pragma unroll
;             for (int m = 0; m < 4; ++m) { const bf16_t* gp = G + (size_t)(row0 + ai * HALF + m * 16) * ldg + col0;
; #pragma unroll
;                 for (int bj = 0; bj < 2; ++bj) { gv[m][bj] = *(const u32x4*)(gp + bj * HALF); hv[m][bj] = *(const u32x4*)(gp + bj * HALF + 2048); } }
;             asm volatile("" ::: "memory");
; #pragma unroll
;             for (int m = 0; m < 4; ++m)
; #pragma unroll
;                 for (int bj = 0; bj < 2; ++bj) { const u32x4 g = gv[m][bj], h = hv[m][bj];
;                     const unsigned gw[4] = {g.x, g.y, g.z, g.w}, hw[4] = {h.x, h.y, h.z, h.w};
; #pragma unroll
;                     for (int e2 = 0; e2 < 4; ++e2) { const float r0 = fmaxf(bflo(gw[e2]), 1e-6f) * __builtin_amdgcn_rcpf(fmaxf(bflo(hw[e2]), 1e-6f)), r1 = fmaxf(bfhi(gw[e2]), 1e-6f) * __builtin_amdgcn_rcpf(fmaxf(bfhi(hw[e2]), 1e-6f));
;                         acc[ai][bj][m][e2 >> 1][(e2 & 1) * 2] *= r0; acc[ai][bj][m][e2 >> 1][(e2 & 1) * 2 + 1] *= r1; } }
	v_lshlrev_b32_e32 v0, 16, v184
	v_max_f32_e32 v214, 0x358637bd, v0
	v_addc_co_u32_e32 v135, vcc, 0, v133, vcc
	global_load_dwordx4 v[140:143], v[134:135], off
	global_load_dwordx4 v[136:139], v[132:133], off offset:256
	s_nop 0
	global_load_dwordx4 v[132:135], v[134:135], off offset:256
	v_lshlrev_b32_e32 v0, 16, v180
	v_max_f32_e32 v0, 0x358637bd, v0
	v_rcp_f32_e32 v220, v0
	v_and_b32_e32 v0, 0xffff0000, v184
	v_max_f32_e32 v215, 0x358637bd, v0
	v_and_b32_e32 v0, 0xffff0000, v180
	v_max_f32_e32 v0, 0x358637bd, v0
	v_rcp_f32_e32 v221, v0
	v_lshlrev_b32_e32 v0, 16, v185
	v_max_f32_e32 v184, 0x358637bd, v0
	v_lshlrev_b32_e32 v0, 16, v181
	v_max_f32_e32 v0, 0x358637bd, v0
	v_rcp_f32_e32 v180, v0
	v_and_b32_e32 v0, 0xffff0000, v185
	v_max_f32_e32 v185, 0x358637bd, v0
	v_and_b32_e32 v0, 0xffff0000, v181
	v_max_f32_e32 v0, 0x358637bd, v0
	v_rcp_f32_e32 v181, v0
	v_lshlrev_b32_e32 v0, 16, v186
	v_pk_mul_f32 v[180:181], v[184:185], v[180:181]
	v_pk_mul_f32 v[214:215], v[214:215], v[220:221]
	v_pk_mul_f32 v[66:67], v[66:67], v[180:181]
	v_max_f32_e32 v180, 0x358637bd, v0
	v_lshlrev_b32_e32 v0, 16, v182
	v_max_f32_e32 v0, 0x358637bd, v0
	v_rcp_f32_e32 v184, v0
	v_and_b32_e32 v0, 0xffff0000, v186
	v_max_f32_e32 v181, 0x358637bd, v0
	v_and_b32_e32 v0, 0xffff0000, v182
	v_max_f32_e32 v0, 0x358637bd, v0
	v_rcp_f32_e32 v185, v0
	v_lshlrev_b32_e32 v0, 16, v187
	v_max_f32_e32 v186, 0x358637bd, v0
	v_lshlrev_b32_e32 v0, 16, v183
	v_max_f32_e32 v0, 0x358637bd, v0
	v_rcp_f32_e32 v182, v0
	v_and_b32_e32 v0, 0xffff0000, v187
	v_max_f32_e32 v187, 0x358637bd, v0
	v_and_b32_e32 v0, 0xffff0000, v183
	v_max_f32_e32 v0, 0x358637bd, v0
	v_rcp_f32_e32 v183, v0
	v_lshlrev_b32_e32 v0, 16, v192
	v_pk_mul_f32 v[180:181], v[180:181], v[184:185]
	v_pk_mul_f32 v[60:61], v[60:61], v[180:181]
	v_max_f32_e32 v180, 0x358637bd, v0
	v_lshlrev_b32_e32 v0, 16, v188
	v_pk_mul_f32 v[182:183], v[186:187], v[182:183]
	v_max_f32_e32 v0, 0x358637bd, v0
	v_pk_mul_f32 v[62:63], v[62:63], v[182:183]
	v_rcp_f32_e32 v182, v0
	v_and_b32_e32 v0, 0xffff0000, v192
	v_max_f32_e32 v181, 0x358637bd, v0
	v_and_b32_e32 v0, 0xffff0000, v188
	v_max_f32_e32 v0, 0x358637bd, v0
	v_rcp_f32_e32 v183, v0
	v_lshlrev_b32_e32 v0, 16, v193
	v_max_f32_e32 v184, 0x358637bd, v0
	v_lshlrev_b32_e32 v0, 16, v189
	v_max_f32_e32 v0, 0x358637bd, v0
	v_rcp_f32_e32 v186, v0
	v_and_b32_e32 v0, 0xffff0000, v193
	v_max_f32_e32 v185, 0x358637bd, v0
	v_and_b32_e32 v0, 0xffff0000, v189
	v_max_f32_e32 v0, 0x358637bd, v0
	v_rcp_f32_e32 v187, v0
	v_lshlrev_b32_e32 v0, 16, v194
	v_pk_mul_f32 v[180:181], v[180:181], v[182:183]
	v_pk_mul_f32 v[32:33], v[32:33], v[180:181]
	v_max_f32_e32 v180, 0x358637bd, v0
	v_lshlrev_b32_e32 v0, 16, v190
	v_pk_mul_f32 v[182:183], v[184:185], v[186:187]
	v_max_f32_e32 v0, 0x358637bd, v0
	v_pk_mul_f32 v[34:35], v[34:35], v[182:183]
	v_rcp_f32_e32 v182, v0
	v_and_b32_e32 v0, 0xffff0000, v194
	v_max_f32_e32 v181, 0x358637bd, v0
	v_and_b32_e32 v0, 0xffff0000, v190
	v_max_f32_e32 v0, 0x358637bd, v0
	v_rcp_f32_e32 v183, v0
	v_lshlrev_b32_e32 v0, 16, v195
	v_max_f32_e32 v184, 0x358637bd, v0
	v_lshlrev_b32_e32 v0, 16, v191
	v_max_f32_e32 v0, 0x358637bd, v0
	v_rcp_f32_e32 v186, v0
	v_and_b32_e32 v0, 0xffff0000, v195
	v_max_f32_e32 v185, 0x358637bd, v0
	v_and_b32_e32 v0, 0xffff0000, v191
	v_max_f32_e32 v0, 0x358637bd, v0
	v_rcp_f32_e32 v187, v0
	v_lshlrev_b32_e32 v0, 16, v176
	v_pk_mul_f32 v[180:181], v[180:181], v[182:183]
	v_pk_mul_f32 v[28:29], v[28:29], v[180:181]
	v_max_f32_e32 v180, 0x358637bd, v0
	v_lshlrev_b32_e32 v0, 16, v172
	v_pk_mul_f32 v[182:183], v[184:185], v[186:187]
	v_max_f32_e32 v0, 0x358637bd, v0
	v_pk_mul_f32 v[30:31], v[30:31], v[182:183]
	v_rcp_f32_e32 v182, v0
	v_and_b32_e32 v0, 0xffff0000, v176
	v_max_f32_e32 v181, 0x358637bd, v0
	v_and_b32_e32 v0, 0xffff0000, v172
	v_max_f32_e32 v0, 0x358637bd, v0
	v_rcp_f32_e32 v183, v0
	v_lshlrev_b32_e32 v0, 16, v177
	v_max_f32_e32 v176, 0x358637bd, v0
	v_lshlrev_b32_e32 v0, 16, v173
	v_max_f32_e32 v0, 0x358637bd, v0
	v_rcp_f32_e32 v172, v0
	v_and_b32_e32 v0, 0xffff0000, v177
	v_max_f32_e32 v177, 0x358637bd, v0
	v_and_b32_e32 v0, 0xffff0000, v173
	v_max_f32_e32 v0, 0x358637bd, v0
	v_rcp_f32_e32 v173, v0
	v_lshlrev_b32_e32 v0, 16, v178
	v_pk_mul_f32 v[180:181], v[180:181], v[182:183]
	v_pk_mul_f32 v[172:173], v[176:177], v[172:173]
	v_pk_mul_f32 v[64:65], v[64:65], v[214:215]
	v_pk_mul_f32 v[58:59], v[58:59], v[172:173]
	v_max_f32_e32 v172, 0x358637bd, v0
	v_lshlrev_b32_e32 v0, 16, v174
	v_max_f32_e32 v0, 0x358637bd, v0
	v_rcp_f32_e32 v176, v0
	v_and_b32_e32 v0, 0xffff0000, v178
	v_max_f32_e32 v173, 0x358637bd, v0
	v_and_b32_e32 v0, 0xffff0000, v174
	v_max_f32_e32 v0, 0x358637bd, v0
	v_rcp_f32_e32 v177, v0
	v_lshlrev_b32_e32 v0, 16, v179
	v_max_f32_e32 v178, 0x358637bd, v0
	v_lshlrev_b32_e32 v0, 16, v175
	v_max_f32_e32 v0, 0x358637bd, v0
	v_rcp_f32_e32 v174, v0
	v_and_b32_e32 v0, 0xffff0000, v179
	v_max_f32_e32 v179, 0x358637bd, v0
	v_and_b32_e32 v0, 0xffff0000, v175
	v_max_f32_e32 v0, 0x358637bd, v0
	v_rcp_f32_e32 v175, v0
	v_lshlrev_b32_e32 v0, 16, v168
	v_pk_mul_f32 v[172:173], v[172:173], v[176:177]
	v_pk_mul_f32 v[52:53], v[52:53], v[172:173]
	v_max_f32_e32 v172, 0x358637bd, v0
	v_lshlrev_b32_e32 v0, 16, v164
	v_pk_mul_f32 v[174:175], v[178:179], v[174:175]
	v_max_f32_e32 v0, 0x358637bd, v0
	v_pk_mul_f32 v[54:55], v[54:55], v[174:175]
	v_rcp_f32_e32 v174, v0
	v_and_b32_e32 v0, 0xffff0000, v168
	v_max_f32_e32 v173, 0x358637bd, v0
	v_and_b32_e32 v0, 0xffff0000, v164
	v_max_f32_e32 v0, 0x358637bd, v0
	v_rcp_f32_e32 v175, v0
	v_lshlrev_b32_e32 v0, 16, v169
	v_max_f32_e32 v168, 0x358637bd, v0
	v_lshlrev_b32_e32 v0, 16, v165
	v_max_f32_e32 v0, 0x358637bd, v0
; __device__ __forceinline__ float bflo(unsigned u) { return __uint_as_float(u << 16); }
; __device__ __forceinline__ float bfhi(unsigned u) { return __uint_as_float(u & 0xffff0000u); }
; __device__ __forceinline__ float bflo(unsigned u) { return __uint_as_float(u << 16); }
; __device__ __forceinline__ float bfhi(unsigned u) { return __uint_as_float(u & 0xffff0000u); }
;     __device__ __forceinline__ void khook(f32x4 (&acc)[2][2][4][2], const Unit& u, int t, int wr, int wc, int fr, int fq) const {
;     ...
;         for (int ai = 0; ai < 2; ++ai) {
;             u32x4 gv[4][2], hv[4][2];
; #pragma unroll
;             for (int m = 0; m < 4; ++m) { const bf16_t* gp = G + (size_t)(row0 + ai * HALF + m * 16) * ldg + col0;
; #pragma unroll
;                 for (int bj = 0; bj < 2; ++bj) { gv[m][bj] = *(const u32x4*)(gp + bj * HALF); hv[m][bj] = *(const u32x4*)(gp + bj * HALF + 2048); } }
;             asm volatile("" ::: "memory");
; #pragma unroll
;             for (int m = 0; m < 4; ++m)
; #pragma unroll
;                 for (int bj = 0; bj < 2; ++bj) { const u32x4 g = gv[m][bj], h = hv[m][bj];
;                     const unsigned gw[4] = {g.x, g.y, g.z, g.w}, hw[4] = {h.x, h.y, h.z, h.w};
; #pragma unroll
;                     for (int e2 = 0; e2 < 4; ++e2) { const float r0 = fmaxf(bflo(gw[e2]), 1e-6f) * __builtin_amdgcn_rcpf(fmaxf(bflo(hw[e2]), 1e-6f)), r1 = fmaxf(bfhi(gw[e2]), 1e-6f) * __builtin_amdgcn_rcpf(fmaxf(bfhi(hw[e2]), 1e-6f));
;                         acc[ai][bj][m][e2 >> 1][(e2 & 1) * 2] *= r0; acc[ai][bj][m][e2 >> 1][(e2 & 1) * 2 + 1] *= r1; } }
	v_rcp_f32_e32 v164, v0
	v_and_b32_e32 v0, 0xffff0000, v169
	v_max_f32_e32 v169, 0x358637bd, v0
	v_and_b32_e32 v0, 0xffff0000, v165
	v_max_f32_e32 v0, 0x358637bd, v0
	v_rcp_f32_e32 v165, v0
	v_lshlrev_b32_e32 v0, 16, v170
	v_pk_mul_f32 v[172:173], v[172:173], v[174:175]
	v_pk_mul_f32 v[164:165], v[168:169], v[164:165]
	v_pk_mul_f32 v[56:57], v[56:57], v[180:181]
	v_pk_mul_f32 v[26:27], v[26:27], v[164:165]
	v_max_f32_e32 v164, 0x358637bd, v0
	v_lshlrev_b32_e32 v0, 16, v166
	v_max_f32_e32 v0, 0x358637bd, v0
	v_rcp_f32_e32 v168, v0
	v_and_b32_e32 v0, 0xffff0000, v170
	v_max_f32_e32 v165, 0x358637bd, v0
	v_and_b32_e32 v0, 0xffff0000, v166
	v_max_f32_e32 v0, 0x358637bd, v0
	v_rcp_f32_e32 v169, v0
	v_lshlrev_b32_e32 v0, 16, v171
	v_max_f32_e32 v170, 0x358637bd, v0
	v_lshlrev_b32_e32 v0, 16, v167
	v_max_f32_e32 v0, 0x358637bd, v0
	v_rcp_f32_e32 v166, v0
	v_and_b32_e32 v0, 0xffff0000, v171
	v_max_f32_e32 v171, 0x358637bd, v0
	v_and_b32_e32 v0, 0xffff0000, v167
	v_max_f32_e32 v0, 0x358637bd, v0
	v_rcp_f32_e32 v167, v0
	v_lshlrev_b32_e32 v0, 16, v160
	v_pk_mul_f32 v[164:165], v[164:165], v[168:169]
	v_pk_mul_f32 v[20:21], v[20:21], v[164:165]
	v_max_f32_e32 v164, 0x358637bd, v0
	v_lshlrev_b32_e32 v0, 16, v156
	v_pk_mul_f32 v[166:167], v[170:171], v[166:167]
	v_max_f32_e32 v0, 0x358637bd, v0
	v_pk_mul_f32 v[22:23], v[22:23], v[166:167]
	v_rcp_f32_e32 v166, v0
	v_and_b32_e32 v0, 0xffff0000, v160
	v_max_f32_e32 v165, 0x358637bd, v0
	v_and_b32_e32 v0, 0xffff0000, v156
	v_max_f32_e32 v0, 0x358637bd, v0
	v_rcp_f32_e32 v167, v0
	v_lshlrev_b32_e32 v0, 16, v161
	v_max_f32_e32 v160, 0x358637bd, v0
	v_lshlrev_b32_e32 v0, 16, v157
	v_max_f32_e32 v0, 0x358637bd, v0
	v_rcp_f32_e32 v156, v0
	v_and_b32_e32 v0, 0xffff0000, v161
	v_max_f32_e32 v161, 0x358637bd, v0
	v_and_b32_e32 v0, 0xffff0000, v157
	v_max_f32_e32 v0, 0x358637bd, v0
	v_rcp_f32_e32 v157, v0
	v_lshlrev_b32_e32 v0, 16, v162
	v_pk_mul_f32 v[164:165], v[164:165], v[166:167]
	v_pk_mul_f32 v[156:157], v[160:161], v[156:157]
	v_pk_mul_f32 v[24:25], v[24:25], v[172:173]
	v_pk_mul_f32 v[50:51], v[50:51], v[156:157]
	v_max_f32_e32 v156, 0x358637bd, v0
	v_lshlrev_b32_e32 v0, 16, v158
	v_max_f32_e32 v0, 0x358637bd, v0
	v_rcp_f32_e32 v160, v0
	v_and_b32_e32 v0, 0xffff0000, v162
	v_max_f32_e32 v157, 0x358637bd, v0
	v_and_b32_e32 v0, 0xffff0000, v158
	v_max_f32_e32 v0, 0x358637bd, v0
	v_rcp_f32_e32 v161, v0
	v_lshlrev_b32_e32 v0, 16, v163
	v_max_f32_e32 v162, 0x358637bd, v0
	v_lshlrev_b32_e32 v0, 16, v159
	v_max_f32_e32 v0, 0x358637bd, v0
	v_rcp_f32_e32 v158, v0
	v_and_b32_e32 v0, 0xffff0000, v163
	v_max_f32_e32 v163, 0x358637bd, v0
	v_and_b32_e32 v0, 0xffff0000, v159
	v_max_f32_e32 v0, 0x358637bd, v0
	v_rcp_f32_e32 v159, v0
	v_lshlrev_b32_e32 v0, 16, v152
	v_pk_mul_f32 v[156:157], v[156:157], v[160:161]
	v_pk_mul_f32 v[44:45], v[44:45], v[156:157]
	v_max_f32_e32 v156, 0x358637bd, v0
	v_lshlrev_b32_e32 v0, 16, v148
	v_pk_mul_f32 v[158:159], v[162:163], v[158:159]
	v_max_f32_e32 v0, 0x358637bd, v0
	v_pk_mul_f32 v[46:47], v[46:47], v[158:159]
	v_rcp_f32_e32 v158, v0
	v_and_b32_e32 v0, 0xffff0000, v152
	v_max_f32_e32 v157, 0x358637bd, v0
	v_and_b32_e32 v0, 0xffff0000, v148
	v_max_f32_e32 v0, 0x358637bd, v0
	v_rcp_f32_e32 v159, v0
	v_lshlrev_b32_e32 v0, 16, v153
	v_max_f32_e32 v152, 0x358637bd, v0
	v_lshlrev_b32_e32 v0, 16, v149
	v_max_f32_e32 v0, 0x358637bd, v0
	v_rcp_f32_e32 v148, v0
	v_and_b32_e32 v0, 0xffff0000, v153
	v_max_f32_e32 v153, 0x358637bd, v0
	v_and_b32_e32 v0, 0xffff0000, v149
	v_max_f32_e32 v0, 0x358637bd, v0
	v_rcp_f32_e32 v149, v0
	v_lshlrev_b32_e32 v0, 16, v154
	v_pk_mul_f32 v[156:157], v[156:157], v[158:159]
	v_pk_mul_f32 v[148:149], v[152:153], v[148:149]
	v_pk_mul_f32 v[48:49], v[48:49], v[164:165]
	v_pk_mul_f32 v[18:19], v[18:19], v[148:149]
	v_max_f32_e32 v148, 0x358637bd, v0
	v_lshlrev_b32_e32 v0, 16, v150
	v_max_f32_e32 v0, 0x358637bd, v0
	v_rcp_f32_e32 v152, v0
	v_and_b32_e32 v0, 0xffff0000, v154
	v_max_f32_e32 v149, 0x358637bd, v0
	v_and_b32_e32 v0, 0xffff0000, v150
	v_max_f32_e32 v0, 0x358637bd, v0
	v_rcp_f32_e32 v153, v0
	v_lshlrev_b32_e32 v0, 16, v155
	v_max_f32_e32 v154, 0x358637bd, v0
	v_lshlrev_b32_e32 v0, 16, v151
	v_max_f32_e32 v0, 0x358637bd, v0
	v_rcp_f32_e32 v150, v0
	v_and_b32_e32 v0, 0xffff0000, v155
	v_max_f32_e32 v155, 0x358637bd, v0
	v_and_b32_e32 v0, 0xffff0000, v151
	v_max_f32_e32 v0, 0x358637bd, v0
	v_rcp_f32_e32 v151, v0
	v_lshlrev_b32_e32 v0, 16, v144
	v_pk_mul_f32 v[148:149], v[148:149], v[152:153]
	v_pk_mul_f32 v[12:13], v[12:13], v[148:149]
	v_max_f32_e32 v148, 0x358637bd, v0
	s_waitcnt vmcnt(0)
; #define PG8_BAR __builtin_amdgcn_s_barrier()
; __device__ __forceinline__ float bflo(unsigned u) { return __uint_as_float(u << 16); }
; __device__ __forceinline__ float bfhi(unsigned u) { return __uint_as_float(u & 0xffff0000u); }
; __device__ __forceinline__ float bflo(unsigned u) { return __uint_as_float(u << 16); }
; __device__ __forceinline__ float bfhi(unsigned u) { return __uint_as_float(u & 0xffff0000u); }
; template <class Epi, class Sched, bool ALIGN_EPI = false, bool SP2 = false>
; __device__ __forceinline__ void gemm_phase(PG8_LAS unsigned char* lds, const int ldk  , const Sched& S, const Epi& E, const int wave_id) {
;     ...
;             if constexpr (Epi::HOOK) { if (E.hook_at(t)) {
;                 if (wr == 0) PG8_BAR;
;                 E.khook(acc, cur, t, wr, wc, fr, fq);
;                 if (wr == 1) PG8_BAR; } }
;     __device__ __forceinline__ void khook(f32x4 (&acc)[2][2][4][2], const Unit& u, int t, int wr, int wc, int fr, int fq) const {
;     ...
;         for (int ai = 0; ai < 2; ++ai) {
;             u32x4 gv[4][2], hv[4][2];
; #pragma unroll
;             for (int m = 0; m < 4; ++m) { const bf16_t* gp = G + (size_t)(row0 + ai * HALF + m * 16) * ldg + col0;
; #pragma unroll
;                 for (int bj = 0; bj < 2; ++bj) { gv[m][bj] = *(const u32x4*)(gp + bj * HALF); hv[m][bj] = *(const u32x4*)(gp + bj * HALF + 2048); } }
;             asm volatile("" ::: "memory");
; #pragma unroll
;             for (int m = 0; m < 4; ++m)
; #pragma unroll
;                 for (int bj = 0; bj < 2; ++bj) { const u32x4 g = gv[m][bj], h = hv[m][bj];
;                     const unsigned gw[4] = {g.x, g.y, g.z, g.w}, hw[4] = {h.x, h.y, h.z, h.w};
; #pragma unroll
;                     for (int e2 = 0; e2 < 4; ++e2) { const float r0 = fmaxf(bflo(gw[e2]), 1e-6f) * __builtin_amdgcn_rcpf(fmaxf(bflo(hw[e2]), 1e-6f)), r1 = fmaxf(bfhi(gw[e2]), 1e-6f) * __builtin_amdgcn_rcpf(fmaxf(bfhi(hw[e2]), 1e-6f));
;                         acc[ai][bj][m][e2 >> 1][(e2 & 1) * 2] *= r0; acc[ai][bj][m][e2 >> 1][(e2 & 1) * 2 + 1] *= r1; } }
	v_lshlrev_b32_e32 v0, 16, v140
	v_pk_mul_f32 v[150:151], v[154:155], v[150:151]
	v_max_f32_e32 v0, 0x358637bd, v0
	v_pk_mul_f32 v[14:15], v[14:15], v[150:151]
	v_rcp_f32_e32 v150, v0
	v_and_b32_e32 v0, 0xffff0000, v144
	v_max_f32_e32 v149, 0x358637bd, v0
	v_and_b32_e32 v0, 0xffff0000, v140
	v_max_f32_e32 v0, 0x358637bd, v0
	v_rcp_f32_e32 v151, v0
	v_lshlrev_b32_e32 v0, 16, v145
	v_max_f32_e32 v144, 0x358637bd, v0
	v_lshlrev_b32_e32 v0, 16, v141
	v_max_f32_e32 v0, 0x358637bd, v0
	v_rcp_f32_e32 v140, v0
	v_and_b32_e32 v0, 0xffff0000, v145
	v_max_f32_e32 v145, 0x358637bd, v0
	v_and_b32_e32 v0, 0xffff0000, v141
	v_max_f32_e32 v0, 0x358637bd, v0
	v_rcp_f32_e32 v141, v0
	v_lshlrev_b32_e32 v0, 16, v146
	v_pk_mul_f32 v[148:149], v[148:149], v[150:151]
	v_pk_mul_f32 v[140:141], v[144:145], v[140:141]
	v_pk_mul_f32 v[16:17], v[16:17], v[156:157]
	v_pk_mul_f32 v[42:43], v[42:43], v[140:141]
	v_max_f32_e32 v140, 0x358637bd, v0
	v_lshlrev_b32_e32 v0, 16, v142
	v_max_f32_e32 v0, 0x358637bd, v0
	v_rcp_f32_e32 v144, v0
	v_and_b32_e32 v0, 0xffff0000, v146
	v_max_f32_e32 v141, 0x358637bd, v0
	v_and_b32_e32 v0, 0xffff0000, v142
	v_max_f32_e32 v0, 0x358637bd, v0
	v_rcp_f32_e32 v145, v0
	v_lshlrev_b32_e32 v0, 16, v147
	v_max_f32_e32 v146, 0x358637bd, v0
	v_lshlrev_b32_e32 v0, 16, v143
	v_max_f32_e32 v0, 0x358637bd, v0
	v_rcp_f32_e32 v142, v0
	v_and_b32_e32 v0, 0xffff0000, v147
	v_max_f32_e32 v147, 0x358637bd, v0
	v_and_b32_e32 v0, 0xffff0000, v143
	v_max_f32_e32 v0, 0x358637bd, v0
	v_rcp_f32_e32 v143, v0
	v_lshlrev_b32_e32 v0, 16, v136
	v_pk_mul_f32 v[140:141], v[140:141], v[144:145]
	v_pk_mul_f32 v[36:37], v[36:37], v[140:141]
	v_max_f32_e32 v140, 0x358637bd, v0
	v_lshlrev_b32_e32 v0, 16, v132
	v_pk_mul_f32 v[142:143], v[146:147], v[142:143]
	v_max_f32_e32 v0, 0x358637bd, v0
	v_pk_mul_f32 v[38:39], v[38:39], v[142:143]
	v_rcp_f32_e32 v142, v0
	v_and_b32_e32 v0, 0xffff0000, v136
	v_max_f32_e32 v141, 0x358637bd, v0
	v_and_b32_e32 v0, 0xffff0000, v132
	v_max_f32_e32 v0, 0x358637bd, v0
	v_rcp_f32_e32 v143, v0
	v_lshlrev_b32_e32 v0, 16, v137
	v_max_f32_e32 v136, 0x358637bd, v0
	v_lshlrev_b32_e32 v0, 16, v133
	v_max_f32_e32 v0, 0x358637bd, v0
	v_rcp_f32_e32 v132, v0
	v_and_b32_e32 v0, 0xffff0000, v137
	v_max_f32_e32 v137, 0x358637bd, v0
	v_and_b32_e32 v0, 0xffff0000, v133
	v_max_f32_e32 v0, 0x358637bd, v0
	v_rcp_f32_e32 v133, v0
	v_lshlrev_b32_e32 v0, 16, v138
	v_pk_mul_f32 v[140:141], v[140:141], v[142:143]
	v_pk_mul_f32 v[132:133], v[136:137], v[132:133]
	v_pk_mul_f32 v[40:41], v[40:41], v[148:149]
	v_pk_mul_f32 v[10:11], v[10:11], v[132:133]
	v_max_f32_e32 v132, 0x358637bd, v0
	v_lshlrev_b32_e32 v0, 16, v134
	v_max_f32_e32 v0, 0x358637bd, v0
	v_rcp_f32_e32 v136, v0
	v_and_b32_e32 v0, 0xffff0000, v138
	v_max_f32_e32 v133, 0x358637bd, v0
	v_and_b32_e32 v0, 0xffff0000, v134
	v_max_f32_e32 v0, 0x358637bd, v0
	v_rcp_f32_e32 v137, v0
	v_lshlrev_b32_e32 v0, 16, v139
	v_max_f32_e32 v138, 0x358637bd, v0
	v_lshlrev_b32_e32 v0, 16, v135
	v_max_f32_e32 v0, 0x358637bd, v0
	v_rcp_f32_e32 v134, v0
	v_and_b32_e32 v0, 0xffff0000, v139
	v_max_f32_e32 v139, 0x358637bd, v0
	v_and_b32_e32 v0, 0xffff0000, v135
	v_max_f32_e32 v0, 0x358637bd, v0
	v_rcp_f32_e32 v135, v0
	v_pk_mul_f32 v[132:133], v[132:133], v[136:137]
	v_pk_mul_f32 v[8:9], v[8:9], v[140:141]
	v_pk_mul_f32 v[4:5], v[4:5], v[132:133]
	v_pk_mul_f32 v[134:135], v[138:139], v[134:135]
	s_andn2_b64 vcc, exec, s[12:13]
	v_pk_mul_f32 v[6:7], v[6:7], v[134:135]
	s_cbranch_vccnz .LBB0_1395
	s_barrier

; __device__ __forceinline__ u32x4 pack8(f32x4 v0, f32x4 v1) { u32x4 w; w.x = cvt_pk_bf16(v0[0], v0[1]); w.y = cvt_pk_bf16(v0[2], v0[3]); w.z = cvt_pk_bf16(v1[0], v1[1]); w.w = cvt_pk_bf16(v1[2], v1[3]); return w; }
; __device__ __forceinline__ float bflo(unsigned u) { return __uint_as_float(u << 16); }
; __device__ __forceinline__ float bfhi(unsigned u) { return __uint_as_float(u & 0xffff0000u); }
;     __device__ __forceinline__ void operator()(const f32x4 (&acc)[2][2][4][2], const Unit& u, int wr, int wc, int fr, int fq) const { if (u.kind == 0) e0(acc, u, wr, wc, fr, fq); else e1(acc, u, wr, wc, fr, fq); }
; __device__ __forceinline__ float bflo(unsigned u) { return __uint_as_float(u << 16); }
; __device__ __forceinline__ float bfhi(unsigned u) { return __uint_as_float(u & 0xffff0000u); }
;     __device__ __forceinline__ void operator()(const f32x4 (&acc)[2][2][4][2], const Unit& u, int wr, int wc, int fr, int fq) const {
;         const int row0 = u.pm * BM + wr * 64 + fr, col0 = u.pn * BM + wc * 32 + 8 * fq;
; #pragma unroll
;         for (int ai = 0; ai < 2; ++ai) {
;             u32x4 gv[4][2];
; #pragma unroll
;             for (int m = 0; m < 4; ++m)
; #pragma unroll
;                 for (int bj = 0; bj < 2; ++bj) gv[m][bj] = *(const u32x4*)(G + (size_t)(row0 + ai * HALF + m * 16) * ldg + col0 + bj * HALF + 3 * 2048);
;             asm volatile("" ::: "memory");
; #pragma unroll
;             for (int m = 0; m < 4; ++m) { const size_t row = (size_t)(row0 + ai * HALF + m * 16);
; #pragma unroll
;                 for (int bj = 0; bj < 2; ++bj) { const int col = col0 + bj * HALF; const u32x4 g = gv[m][bj];
;                     const f32x4 v0 = acc[ai][bj][m][0] * (f32x4){fmaxf(bflo(g.x), 1e-6f), fmaxf(bfhi(g.x), 1e-6f), fmaxf(bflo(g.y), 1e-6f), fmaxf(bfhi(g.y), 1e-6f)};
;                     const f32x4 v1 = acc[ai][bj][m][1] * (f32x4){fmaxf(bflo(g.z), 1e-6f), fmaxf(bfhi(g.z), 1e-6f), fmaxf(bflo(g.w), 1e-6f), fmaxf(bfhi(g.w), 1e-6f)};
;                     *(u32x4*)(Mo + row * 2048 + col) = pack8(v0, v1); } }
;         }
;     }
.LBB0_1398:
	v_ashrrev_i32_e32 v209, 31, v208
	v_lshlrev_b64 v[160:161], 1, v[208:209]
	v_lshl_add_u64 v[162:163], s[2:3], 0, v[160:161]
	s_movk_i32 s6, 0x6c00
	v_mad_i64_i32 v[132:133], s[4:5], v2, s6, v[162:163]
	v_add_co_u32_e32 v132, vcc, 0x3000, v132
	v_or_b32_e32 v168, 16, v2
	s_nop 0
	v_addc_co_u32_e32 v133, vcc, 0, v133, vcc
	global_load_dwordx4 v[170:173], v[132:133], off
	global_load_dwordx4 v[156:159], v[132:133], off offset:256
	v_mad_i64_i32 v[132:133], s[4:5], v168, s6, v[162:163]
	v_add_co_u32_e32 v132, vcc, 0x3000, v132
	v_or_b32_e32 v166, 32, v2
	s_nop 0
	v_addc_co_u32_e32 v133, vcc, 0, v133, vcc
	global_load_dwordx4 v[152:155], v[132:133], off
	global_load_dwordx4 v[148:151], v[132:133], off offset:256
	v_mad_i64_i32 v[132:133], s[4:5], v166, s6, v[162:163]
	v_add_co_u32_e32 v132, vcc, 0x3000, v132
	v_ashrrev_i32_e32 v3, 31, v2
	s_nop 0
	v_addc_co_u32_e32 v133, vcc, 0, v133, vcc
	global_load_dwordx4 v[144:147], v[132:133], off
	global_load_dwordx4 v[140:143], v[132:133], off offset:256
	v_or_b32_e32 v164, 48, v2
	v_mad_i64_i32 v[132:133], s[4:5], v164, s6, v[162:163]
	v_lshlrev_b64 v[176:177], 12, v[2:3]
	v_add_co_u32_e32 v132, vcc, 0x3000, v132
	v_ashrrev_i32_e32 v169, 31, v168
	s_nop 0
	v_addc_co_u32_e32 v133, vcc, 0, v133, vcc
	global_load_dwordx4 v[136:139], v[132:133], off
	s_nop 0
	global_load_dwordx4 v[132:135], v[132:133], off offset:256
	v_ashrrev_i32_e32 v167, 31, v166
	v_ashrrev_i32_e32 v165, 31, v164
	s_movk_i32 s7, 0x3000
	s_add_u32 s34, s51, 0xffffff00
	s_addc_u32 s35, s52, -1
	s_waitcnt vmcnt(0)
	v_lshlrev_b32_e32 v0, 16, v170
	v_max_f32_e32 v174, 0x358637bd, v0
	v_and_b32_e32 v0, 0xffff0000, v170
	v_max_f32_e32 v175, 0x358637bd, v0
	v_lshlrev_b32_e32 v0, 16, v171
	v_max_f32_e32 v170, 0x358637bd, v0
	v_and_b32_e32 v0, 0xffff0000, v171
	v_max_f32_e32 v171, 0x358637bd, v0
	v_lshlrev_b32_e32 v0, 16, v172
	v_max_f32_e32 v178, 0x358637bd, v0
	v_and_b32_e32 v0, 0xffff0000, v172
	v_max_f32_e32 v179, 0x358637bd, v0
	v_lshlrev_b32_e32 v0, 16, v173
	v_max_f32_e32 v172, 0x358637bd, v0
	v_and_b32_e32 v0, 0xffff0000, v173
	v_pk_mul_f32 v[170:171], v[130:131], v[170:171]
	v_max_f32_e32 v173, 0x358637bd, v0
	v_pk_mul_f32 v[174:175], v[128:129], v[174:175]
	v_pk_mul_f32 v[180:181], v[126:127], v[172:173]
	v_pk_mul_f32 v[178:179], v[124:125], v[178:179]
	v_cvt_pk_bf16_f32 v173, v170, v171
	v_lshl_add_u64 v[170:171], s[16:17], 0, v[176:177]
	v_lshlrev_b32_e32 v0, 16, v156
	v_cvt_pk_bf16_f32 v172, v174, v175
	v_cvt_pk_bf16_f32 v174, v178, v179
	v_cvt_pk_bf16_f32 v175, v180, v181
	v_lshl_add_u64 v[170:171], v[170:171], 0, v[160:161]
	global_store_dwordx4 v[170:171], v[172:175], off
	s_nop 1
	v_max_f32_e32 v172, 0x358637bd, v0
	v_and_b32_e32 v0, 0xffff0000, v156
	v_max_f32_e32 v173, 0x358637bd, v0
	v_lshlrev_b32_e32 v0, 16, v157
	v_max_f32_e32 v156, 0x358637bd, v0
	v_and_b32_e32 v0, 0xffff0000, v157
	v_max_f32_e32 v157, 0x358637bd, v0
	v_lshlrev_b32_e32 v0, 16, v158
	v_pk_mul_f32 v[174:175], v[98:99], v[156:157]
	v_pk_mul_f32 v[156:157], v[96:97], v[172:173]
	v_max_f32_e32 v172, 0x358637bd, v0
	v_and_b32_e32 v0, 0xffff0000, v158
	v_max_f32_e32 v173, 0x358637bd, v0
	v_lshlrev_b32_e32 v0, 16, v159
	v_max_f32_e32 v158, 0x358637bd, v0
	v_and_b32_e32 v0, 0xffff0000, v159
	v_max_f32_e32 v159, 0x358637bd, v0
	v_pk_mul_f32 v[176:177], v[94:95], v[158:159]
	v_pk_mul_f32 v[158:159], v[92:93], v[172:173]
	v_lshlrev_b32_e32 v0, 16, v152
	v_cvt_pk_bf16_f32 v156, v156, v157
	v_cvt_pk_bf16_f32 v157, v174, v175
	v_cvt_pk_bf16_f32 v158, v158, v159
	v_cvt_pk_bf16_f32 v159, v176, v177
	global_store_dwordx4 v[170:171], v[156:159], off offset:256
	v_add_u32_e32 v172, 0xa0, v2
	v_ashrrev_i32_e32 v173, 31, v172
	v_max_f32_e32 v158, 0x358637bd, v0
	v_and_b32_e32 v0, 0xffff0000, v152
	v_max_f32_e32 v159, 0x358637bd, v0
	v_lshlrev_b32_e32 v0, 16, v153
	v_max_f32_e32 v152, 0x358637bd, v0
	v_and_b32_e32 v0, 0xffff0000, v153
	v_max_f32_e32 v153, 0x358637bd, v0
	v_lshlrev_b32_e32 v0, 16, v154
	v_lshlrev_b64 v[156:157], 12, v[168:169]
	v_pk_mul_f32 v[168:169], v[122:123], v[152:153]
	v_pk_mul_f32 v[152:153], v[120:121], v[158:159]
	v_max_f32_e32 v158, 0x358637bd, v0
	v_and_b32_e32 v0, 0xffff0000, v154
	v_max_f32_e32 v159, 0x358637bd, v0
	v_lshlrev_b32_e32 v0, 16, v155
	v_max_f32_e32 v154, 0x358637bd, v0
	v_and_b32_e32 v0, 0xffff0000, v155
	v_max_f32_e32 v155, 0x358637bd, v0
	v_pk_mul_f32 v[170:171], v[118:119], v[154:155]
	v_pk_mul_f32 v[154:155], v[116:117], v[158:159]
	v_lshl_add_u64 v[156:157], s[16:17], 0, v[156:157]
	v_lshlrev_b32_e32 v0, 16, v148
	v_cvt_pk_bf16_f32 v152, v152, v153
	v_cvt_pk_bf16_f32 v153, v168, v169
	v_cvt_pk_bf16_f32 v154, v154, v155
	v_cvt_pk_bf16_f32 v155, v170, v171
	v_lshl_add_u64 v[156:157], v[156:157], 0, v[160:161]
	global_store_dwordx4 v[156:157], v[152:155], off
	v_add_u32_e32 v168, 0x80, v2
	v_add_u32_e32 v170, 0x90, v2
	v_max_f32_e32 v152, 0x358637bd, v0
	v_and_b32_e32 v0, 0xffff0000, v148
	v_max_f32_e32 v153, 0x358637bd, v0
	v_lshlrev_b32_e32 v0, 16, v149
	v_max_f32_e32 v148, 0x358637bd, v0
	v_and_b32_e32 v0, 0xffff0000, v149
	v_max_f32_e32 v149, 0x358637bd, v0
	v_lshlrev_b32_e32 v0, 16, v150
	v_pk_mul_f32 v[154:155], v[90:91], v[148:149]
	v_pk_mul_f32 v[148:149], v[88:89], v[152:153]
	v_max_f32_e32 v152, 0x358637bd, v0
	v_and_b32_e32 v0, 0xffff0000, v150
	v_max_f32_e32 v153, 0x358637bd, v0
	v_lshlrev_b32_e32 v0, 16, v151
	v_max_f32_e32 v150, 0x358637bd, v0
	v_and_b32_e32 v0, 0xffff0000, v151
	v_max_f32_e32 v151, 0x358637bd, v0
	v_pk_mul_f32 v[158:159], v[86:87], v[150:151]
	v_pk_mul_f32 v[150:151], v[84:85], v[152:153]
	v_lshlrev_b32_e32 v0, 16, v144
	v_cvt_pk_bf16_f32 v148, v148, v149
	v_cvt_pk_bf16_f32 v149, v154, v155
; __device__ __forceinline__ u32x4 pack8(f32x4 v0, f32x4 v1) { u32x4 w; w.x = cvt_pk_bf16(v0[0], v0[1]); w.y = cvt_pk_bf16(v0[2], v0[3]); w.z = cvt_pk_bf16(v1[0], v1[1]); w.w = cvt_pk_bf16(v1[2], v1[3]); return w; }
; __device__ __forceinline__ float bflo(unsigned u) { return __uint_as_float(u << 16); }
; __device__ __forceinline__ float bfhi(unsigned u) { return __uint_as_float(u & 0xffff0000u); }
;     __device__ __forceinline__ void operator()(const f32x4 (&acc)[2][2][4][2], const Unit& u, int wr, int wc, int fr, int fq) const { if (u.kind == 0) e0(acc, u, wr, wc, fr, fq); else e1(acc, u, wr, wc, fr, fq); }
; __device__ __forceinline__ float bflo(unsigned u) { return __uint_as_float(u << 16); }
; __device__ __forceinline__ float bfhi(unsigned u) { return __uint_as_float(u & 0xffff0000u); }
;     __device__ __forceinline__ void operator()(const f32x4 (&acc)[2][2][4][2], const Unit& u, int wr, int wc, int fr, int fq) const {
;         const int row0 = u.pm * BM + wr * 64 + fr, col0 = u.pn * BM + wc * 32 + 8 * fq;
; #pragma unroll
;         for (int ai = 0; ai < 2; ++ai) {
;             u32x4 gv[4][2];
; #pragma unroll
;             for (int m = 0; m < 4; ++m)
; #pragma unroll
;                 for (int bj = 0; bj < 2; ++bj) gv[m][bj] = *(const u32x4*)(G + (size_t)(row0 + ai * HALF + m * 16) * ldg + col0 + bj * HALF + 3 * 2048);
;             asm volatile("" ::: "memory");
; #pragma unroll
;             for (int m = 0; m < 4; ++m) { const size_t row = (size_t)(row0 + ai * HALF + m * 16);
; #pragma unroll
;                 for (int bj = 0; bj < 2; ++bj) { const int col = col0 + bj * HALF; const u32x4 g = gv[m][bj];
;                     const f32x4 v0 = acc[ai][bj][m][0] * (f32x4){fmaxf(bflo(g.x), 1e-6f), fmaxf(bfhi(g.x), 1e-6f), fmaxf(bflo(g.y), 1e-6f), fmaxf(bfhi(g.y), 1e-6f)};
;                     const f32x4 v1 = acc[ai][bj][m][1] * (f32x4){fmaxf(bflo(g.z), 1e-6f), fmaxf(bfhi(g.z), 1e-6f), fmaxf(bflo(g.w), 1e-6f), fmaxf(bfhi(g.w), 1e-6f)};
;                     *(u32x4*)(Mo + row * 2048 + col) = pack8(v0, v1); } }
;         }
;     }
	v_cvt_pk_bf16_f32 v150, v150, v151
	v_cvt_pk_bf16_f32 v151, v158, v159
	global_store_dwordx4 v[156:157], v[148:151], off offset:256
	v_ashrrev_i32_e32 v169, 31, v168
	v_add_u32_e32 v2, 0xb0, v2
	v_max_f32_e32 v150, 0x358637bd, v0
	v_and_b32_e32 v0, 0xffff0000, v144
	v_max_f32_e32 v151, 0x358637bd, v0
	v_lshlrev_b32_e32 v0, 16, v145
	v_max_f32_e32 v144, 0x358637bd, v0
	v_and_b32_e32 v0, 0xffff0000, v145
	v_max_f32_e32 v145, 0x358637bd, v0
	v_lshlrev_b32_e32 v0, 16, v146
	v_pk_mul_f32 v[152:153], v[114:115], v[144:145]
	v_pk_mul_f32 v[144:145], v[112:113], v[150:151]
	v_max_f32_e32 v150, 0x358637bd, v0
	v_and_b32_e32 v0, 0xffff0000, v146
	v_max_f32_e32 v151, 0x358637bd, v0
	v_lshlrev_b32_e32 v0, 16, v147
	v_max_f32_e32 v146, 0x358637bd, v0
	v_and_b32_e32 v0, 0xffff0000, v147
	v_lshlrev_b64 v[148:149], 12, v[166:167]
	v_max_f32_e32 v147, 0x358637bd, v0
	v_pk_mul_f32 v[154:155], v[110:111], v[146:147]
	v_pk_mul_f32 v[146:147], v[108:109], v[150:151]
	v_lshl_add_u64 v[148:149], s[16:17], 0, v[148:149]
	v_lshlrev_b32_e32 v0, 16, v140
	v_cvt_pk_bf16_f32 v144, v144, v145
	v_cvt_pk_bf16_f32 v145, v152, v153
	v_cvt_pk_bf16_f32 v146, v146, v147
	v_cvt_pk_bf16_f32 v147, v154, v155
	v_lshl_add_u64 v[148:149], v[148:149], 0, v[160:161]
	global_store_dwordx4 v[148:149], v[144:147], off
	v_ashrrev_i32_e32 v171, 31, v170
	v_ashrrev_i32_e32 v3, 31, v2
	v_max_f32_e32 v144, 0x358637bd, v0
	v_and_b32_e32 v0, 0xffff0000, v140
	v_max_f32_e32 v145, 0x358637bd, v0
	v_lshlrev_b32_e32 v0, 16, v141
	v_max_f32_e32 v140, 0x358637bd, v0
	v_and_b32_e32 v0, 0xffff0000, v141
	v_max_f32_e32 v141, 0x358637bd, v0
	v_lshlrev_b32_e32 v0, 16, v142
	v_pk_mul_f32 v[146:147], v[82:83], v[140:141]
	v_pk_mul_f32 v[140:141], v[80:81], v[144:145]
	v_max_f32_e32 v144, 0x358637bd, v0
	v_and_b32_e32 v0, 0xffff0000, v142
	v_max_f32_e32 v145, 0x358637bd, v0
	v_lshlrev_b32_e32 v0, 16, v143
	v_max_f32_e32 v142, 0x358637bd, v0
	v_and_b32_e32 v0, 0xffff0000, v143
	v_max_f32_e32 v143, 0x358637bd, v0
	v_pk_mul_f32 v[150:151], v[78:79], v[142:143]
	v_pk_mul_f32 v[142:143], v[76:77], v[144:145]
	v_lshlrev_b32_e32 v0, 16, v136
	v_cvt_pk_bf16_f32 v140, v140, v141
	v_cvt_pk_bf16_f32 v141, v146, v147
	v_cvt_pk_bf16_f32 v142, v142, v143
	v_cvt_pk_bf16_f32 v143, v150, v151
	global_store_dwordx4 v[148:149], v[140:143], off offset:256
	s_nop 1
	v_max_f32_e32 v142, 0x358637bd, v0
	v_and_b32_e32 v0, 0xffff0000, v136
	v_max_f32_e32 v143, 0x358637bd, v0
	v_lshlrev_b32_e32 v0, 16, v137
	v_max_f32_e32 v136, 0x358637bd, v0
	v_and_b32_e32 v0, 0xffff0000, v137
	v_max_f32_e32 v137, 0x358637bd, v0
	v_lshlrev_b32_e32 v0, 16, v138
	v_pk_mul_f32 v[144:145], v[106:107], v[136:137]
	v_pk_mul_f32 v[136:137], v[104:105], v[142:143]
	v_max_f32_e32 v142, 0x358637bd, v0
	v_and_b32_e32 v0, 0xffff0000, v138
	v_max_f32_e32 v143, 0x358637bd, v0
	v_lshlrev_b32_e32 v0, 16, v139
	v_max_f32_e32 v138, 0x358637bd, v0
	v_and_b32_e32 v0, 0xffff0000, v139
	v_lshlrev_b64 v[140:141], 12, v[164:165]
	v_max_f32_e32 v139, 0x358637bd, v0
	v_pk_mul_f32 v[146:147], v[102:103], v[138:139]
	v_pk_mul_f32 v[138:139], v[100:101], v[142:143]
	v_lshl_add_u64 v[140:141], s[16:17], 0, v[140:141]
	v_lshlrev_b32_e32 v0, 16, v132
	v_cvt_pk_bf16_f32 v136, v136, v137
	v_cvt_pk_bf16_f32 v137, v144, v145
	v_cvt_pk_bf16_f32 v138, v138, v139
	v_cvt_pk_bf16_f32 v139, v146, v147
	v_lshl_add_u64 v[140:141], v[140:141], 0, v[160:161]
	global_store_dwordx4 v[140:141], v[136:139], off
	s_nop 1
	v_max_f32_e32 v136, 0x358637bd, v0
	v_and_b32_e32 v0, 0xffff0000, v132
	v_max_f32_e32 v137, 0x358637bd, v0
	v_lshlrev_b32_e32 v0, 16, v133
	v_max_f32_e32 v132, 0x358637bd, v0
	v_and_b32_e32 v0, 0xffff0000, v133
	v_max_f32_e32 v133, 0x358637bd, v0
	v_lshlrev_b32_e32 v0, 16, v134
	v_pk_mul_f32 v[138:139], v[74:75], v[132:133]
	v_pk_mul_f32 v[132:133], v[72:73], v[136:137]
	v_max_f32_e32 v136, 0x358637bd, v0
	v_and_b32_e32 v0, 0xffff0000, v134
	v_max_f32_e32 v137, 0x358637bd, v0
	v_lshlrev_b32_e32 v0, 16, v135
	v_max_f32_e32 v134, 0x358637bd, v0
	v_and_b32_e32 v0, 0xffff0000, v135
	v_max_f32_e32 v135, 0x358637bd, v0
	v_pk_mul_f32 v[142:143], v[70:71], v[134:135]
	v_pk_mul_f32 v[134:135], v[68:69], v[136:137]
	v_cvt_pk_bf16_f32 v132, v132, v133
	v_cvt_pk_bf16_f32 v133, v138, v139
	v_cvt_pk_bf16_f32 v134, v134, v135
	v_cvt_pk_bf16_f32 v135, v142, v143
	global_store_dwordx4 v[140:141], v[132:135], off offset:256
	s_nop 1
	v_mad_i64_i32 v[132:133], s[4:5], v168, s6, v[162:163]
	v_add_co_u32_e32 v132, vcc, s7, v132
	s_nop 1
	v_addc_co_u32_e32 v133, vcc, 0, v133, vcc
	global_load_dwordx4 v[144:147], v[132:133], off
	global_load_dwordx4 v[148:151], v[132:133], off offset:256
	v_mad_i64_i32 v[132:133], s[4:5], v170, s6, v[162:163]
	v_add_co_u32_e32 v132, vcc, s7, v132
	s_waitcnt vmcnt(1)
	v_lshlrev_b32_e32 v0, 16, v144
	v_addc_co_u32_e32 v133, vcc, 0, v133, vcc
	global_load_dwordx4 v[152:155], v[132:133], off
	global_load_dwordx4 v[156:159], v[132:133], off offset:256
	v_mad_i64_i32 v[132:133], s[4:5], v172, s6, v[162:163]
	v_add_co_u32_e32 v132, vcc, s7, v132
	s_nop 0
	s_nop 0
	v_addc_co_u32_e32 v133, vcc, 0, v133, vcc
	global_load_dwordx4 v[164:167], v[132:133], off
	global_load_dwordx4 v[140:143], v[132:133], off offset:256
	v_mad_i64_i32 v[132:133], s[4:5], v2, s6, v[162:163]
	v_lshlrev_b64 v[162:163], 12, v[168:169]
	v_max_f32_e32 v168, 0x358637bd, v0
	v_and_b32_e32 v0, 0xffff0000, v144
	v_max_f32_e32 v169, 0x358637bd, v0
	v_lshlrev_b32_e32 v0, 16, v145
	v_max_f32_e32 v144, 0x358637bd, v0
	v_and_b32_e32 v0, 0xffff0000, v145
	v_max_f32_e32 v145, 0x358637bd, v0
	v_lshlrev_b32_e32 v0, 16, v146
	v_pk_mul_f32 v[174:175], v[66:67], v[144:145]
	v_pk_mul_f32 v[144:145], v[64:65], v[168:169]
	v_max_f32_e32 v168, 0x358637bd, v0
	v_and_b32_e32 v0, 0xffff0000, v146
	v_max_f32_e32 v169, 0x358637bd, v0
	v_lshlrev_b32_e32 v0, 16, v147
	v_max_f32_e32 v146, 0x358637bd, v0
	v_and_b32_e32 v0, 0xffff0000, v147
	v_max_f32_e32 v147, 0x358637bd, v0
	v_add_co_u32_e32 v132, vcc, s7, v132
	v_pk_mul_f32 v[176:177], v[62:63], v[146:147]
	v_pk_mul_f32 v[146:147], v[60:61], v[168:169]
	v_lshl_add_u64 v[162:163], s[16:17], 0, v[162:163]
	s_waitcnt vmcnt(4)
; __device__ __forceinline__ u32x4 pack8(f32x4 v0, f32x4 v1) { u32x4 w; w.x = cvt_pk_bf16(v0[0], v0[1]); w.y = cvt_pk_bf16(v0[2], v0[3]); w.z = cvt_pk_bf16(v1[0], v1[1]); w.w = cvt_pk_bf16(v1[2], v1[3]); return w; }
; __device__ __forceinline__ float bflo(unsigned u) { return __uint_as_float(u << 16); }
; __device__ __forceinline__ float bfhi(unsigned u) { return __uint_as_float(u & 0xffff0000u); }
;     __device__ __forceinline__ void operator()(const f32x4 (&acc)[2][2][4][2], const Unit& u, int wr, int wc, int fr, int fq) const { if (u.kind == 0) e0(acc, u, wr, wc, fr, fq); else e1(acc, u, wr, wc, fr, fq); }
; __device__ __forceinline__ float bflo(unsigned u) { return __uint_as_float(u << 16); }
; __device__ __forceinline__ float bfhi(unsigned u) { return __uint_as_float(u & 0xffff0000u); }
;     __device__ __forceinline__ void operator()(const f32x4 (&acc)[2][2][4][2], const Unit& u, int wr, int wc, int fr, int fq) const {
;         const int row0 = u.pm * BM + wr * 64 + fr, col0 = u.pn * BM + wc * 32 + 8 * fq;
; #pragma unroll
;         for (int ai = 0; ai < 2; ++ai) {
;             u32x4 gv[4][2];
; #pragma unroll
;             for (int m = 0; m < 4; ++m)
; #pragma unroll
;                 for (int bj = 0; bj < 2; ++bj) gv[m][bj] = *(const u32x4*)(G + (size_t)(row0 + ai * HALF + m * 16) * ldg + col0 + bj * HALF + 3 * 2048);
;             asm volatile("" ::: "memory");
; #pragma unroll
;             for (int m = 0; m < 4; ++m) { const size_t row = (size_t)(row0 + ai * HALF + m * 16);
; #pragma unroll
;                 for (int bj = 0; bj < 2; ++bj) { const int col = col0 + bj * HALF; const u32x4 g = gv[m][bj];
;                     const f32x4 v0 = acc[ai][bj][m][0] * (f32x4){fmaxf(bflo(g.x), 1e-6f), fmaxf(bfhi(g.x), 1e-6f), fmaxf(bflo(g.y), 1e-6f), fmaxf(bfhi(g.y), 1e-6f)};
;                     const f32x4 v1 = acc[ai][bj][m][1] * (f32x4){fmaxf(bflo(g.z), 1e-6f), fmaxf(bfhi(g.z), 1e-6f), fmaxf(bflo(g.w), 1e-6f), fmaxf(bfhi(g.w), 1e-6f)};
;                     *(u32x4*)(Mo + row * 2048 + col) = pack8(v0, v1); } }
;         }
;     }
	v_lshlrev_b32_e32 v0, 16, v148
	v_addc_co_u32_e32 v133, vcc, 0, v133, vcc
	v_cvt_pk_bf16_f32 v144, v144, v145
	v_cvt_pk_bf16_f32 v145, v174, v175
	v_cvt_pk_bf16_f32 v146, v146, v147
	v_cvt_pk_bf16_f32 v147, v176, v177
	v_lshl_add_u64 v[162:163], v[162:163], 0, v[160:161]
	global_load_dwordx4 v[136:139], v[132:133], off
	s_nop 0
	global_load_dwordx4 v[132:135], v[132:133], off offset:256
	global_store_dwordx4 v[162:163], v[144:147], off
	v_lshlrev_b64 v[2:3], 12, v[2:3]
	v_lshl_add_u64 v[2:3], s[16:17], 0, v[2:3]
	v_max_f32_e32 v144, 0x358637bd, v0
	v_and_b32_e32 v0, 0xffff0000, v148
	v_max_f32_e32 v145, 0x358637bd, v0
	v_lshlrev_b32_e32 v0, 16, v149
	v_max_f32_e32 v146, 0x358637bd, v0
	v_and_b32_e32 v0, 0xffff0000, v149
	v_max_f32_e32 v147, 0x358637bd, v0
	v_lshlrev_b32_e32 v0, 16, v150
	v_max_f32_e32 v148, 0x358637bd, v0
	v_and_b32_e32 v0, 0xffff0000, v150
	v_max_f32_e32 v149, 0x358637bd, v0
	v_lshlrev_b32_e32 v0, 16, v151
	v_max_f32_e32 v150, 0x358637bd, v0
	v_and_b32_e32 v0, 0xffff0000, v151
	v_max_f32_e32 v151, 0x358637bd, v0
	v_pk_mul_f32 v[146:147], v[34:35], v[146:147]
	v_pk_mul_f32 v[144:145], v[32:33], v[144:145]
	v_pk_mul_f32 v[150:151], v[30:31], v[150:151]
	v_pk_mul_f32 v[148:149], v[28:29], v[148:149]
	s_waitcnt vmcnt(6)
	v_lshlrev_b32_e32 v0, 16, v152
	v_cvt_pk_bf16_f32 v144, v144, v145
	v_cvt_pk_bf16_f32 v145, v146, v147
	v_cvt_pk_bf16_f32 v146, v148, v149
	v_cvt_pk_bf16_f32 v147, v150, v151
	global_store_dwordx4 v[162:163], v[144:147], off offset:256
	v_lshlrev_b64 v[148:149], 12, v[170:171]
	v_lshl_add_u64 v[148:149], s[16:17], 0, v[148:149]
	v_max_f32_e32 v144, 0x358637bd, v0
	v_and_b32_e32 v0, 0xffff0000, v152
	v_max_f32_e32 v145, 0x358637bd, v0
	v_lshlrev_b32_e32 v0, 16, v153
	v_max_f32_e32 v146, 0x358637bd, v0
	v_and_b32_e32 v0, 0xffff0000, v153
	v_max_f32_e32 v147, 0x358637bd, v0
	v_lshlrev_b32_e32 v0, 16, v154
	v_max_f32_e32 v150, 0x358637bd, v0
	v_and_b32_e32 v0, 0xffff0000, v154
	v_max_f32_e32 v151, 0x358637bd, v0
	v_lshlrev_b32_e32 v0, 16, v155
	v_max_f32_e32 v152, 0x358637bd, v0
	v_and_b32_e32 v0, 0xffff0000, v155
	v_max_f32_e32 v153, 0x358637bd, v0
	v_pk_mul_f32 v[146:147], v[58:59], v[146:147]
	v_pk_mul_f32 v[144:145], v[56:57], v[144:145]
	v_pk_mul_f32 v[152:153], v[54:55], v[152:153]
	v_pk_mul_f32 v[150:151], v[52:53], v[150:151]
	s_waitcnt vmcnt(6)
	v_lshlrev_b32_e32 v0, 16, v156
	v_cvt_pk_bf16_f32 v144, v144, v145
	v_cvt_pk_bf16_f32 v145, v146, v147
	v_cvt_pk_bf16_f32 v146, v150, v151
	v_cvt_pk_bf16_f32 v147, v152, v153
	v_lshl_add_u64 v[148:149], v[148:149], 0, v[160:161]
	global_store_dwordx4 v[148:149], v[144:147], off
	v_lshl_add_u64 v[2:3], v[2:3], 0, v[160:161]
	s_and_b64 vcc, exec, s[36:37]
	v_max_f32_e32 v144, 0x358637bd, v0
	v_and_b32_e32 v0, 0xffff0000, v156
	v_max_f32_e32 v145, 0x358637bd, v0
	v_lshlrev_b32_e32 v0, 16, v157
	v_max_f32_e32 v146, 0x358637bd, v0
	v_and_b32_e32 v0, 0xffff0000, v157
	v_max_f32_e32 v147, 0x358637bd, v0
	v_lshlrev_b32_e32 v0, 16, v158
	v_max_f32_e32 v150, 0x358637bd, v0
	v_and_b32_e32 v0, 0xffff0000, v158
	v_max_f32_e32 v151, 0x358637bd, v0
	v_lshlrev_b32_e32 v0, 16, v159
	v_max_f32_e32 v152, 0x358637bd, v0
	v_and_b32_e32 v0, 0xffff0000, v159
	v_max_f32_e32 v153, 0x358637bd, v0
	v_pk_mul_f32 v[146:147], v[26:27], v[146:147]
	v_pk_mul_f32 v[144:145], v[24:25], v[144:145]
	v_pk_mul_f32 v[152:153], v[22:23], v[152:153]
	v_pk_mul_f32 v[150:151], v[20:21], v[150:151]
	s_waitcnt vmcnt(6)
; #define PG8_BAR __builtin_amdgcn_s_barrier()
; __device__ __forceinline__ u32x4 pack8(f32x4 v0, f32x4 v1) { u32x4 w; w.x = cvt_pk_bf16(v0[0], v0[1]); w.y = cvt_pk_bf16(v0[2], v0[3]); w.z = cvt_pk_bf16(v1[0], v1[1]); w.w = cvt_pk_bf16(v1[2], v1[3]); return w; }
; __device__ __forceinline__ float bflo(unsigned u) { return __uint_as_float(u << 16); }
; __device__ __forceinline__ float bfhi(unsigned u) { return __uint_as_float(u & 0xffff0000u); }
; template <class Epi, class Sched, bool ALIGN_EPI = false, bool SP2 = false>
; __device__ __forceinline__ void gemm_phase(PG8_LAS unsigned char* lds, const int ldk  , const Sched& S, const Epi& E, const int wave_id) {
;     ...
;         if (!has_next) break;
; #pragma unroll
;         for (int a = 0; a < 2; ++a)
; #pragma unroll
;             for (int b = 0; b < 2; ++b)
; #pragma unroll
;                 for (int m = 0; m < 4; ++m)
; #pragma unroll
;                     for (int n = 0; n < 2; ++n) acc[a][b][m][n] = (f32x4){0.f, 0.f, 0.f, 0.f};
;         cur = nxt; cA = nA; cB = nB; ++ui; nt = S.nt(cur);
;         if constexpr (ALIGN_EPI) { if (wr == 1) PG8_BAR; }
;     __device__ __forceinline__ void operator()(const f32x4 (&acc)[2][2][4][2], const Unit& u, int wr, int wc, int fr, int fq) const {
;         const int row0 = u.pm * BM + wr * 64 + fr, col0 = u.pn * BM + wc * 32 + 8 * fq;
; #pragma unroll
;         for (int ai = 0; ai < 2; ++ai) {
;             u32x4 gv[4][2];
; #pragma unroll
;             for (int m = 0; m < 4; ++m)
; #pragma unroll
;                 for (int bj = 0; bj < 2; ++bj) gv[m][bj] = *(const u32x4*)(G + (size_t)(row0 + ai * HALF + m * 16) * ldg + col0 + bj * HALF + 3 * 2048);
;             asm volatile("" ::: "memory");
; #pragma unroll
;             for (int m = 0; m < 4; ++m) { const size_t row = (size_t)(row0 + ai * HALF + m * 16);
; #pragma unroll
;                 for (int bj = 0; bj < 2; ++bj) { const int col = col0 + bj * HALF; const u32x4 g = gv[m][bj];
;                     const f32x4 v0 = acc[ai][bj][m][0] * (f32x4){fmaxf(bflo(g.x), 1e-6f), fmaxf(bfhi(g.x), 1e-6f), fmaxf(bflo(g.y), 1e-6f), fmaxf(bfhi(g.y), 1e-6f)};
;                     const f32x4 v1 = acc[ai][bj][m][1] * (f32x4){fmaxf(bflo(g.z), 1e-6f), fmaxf(bfhi(g.z), 1e-6f), fmaxf(bflo(g.w), 1e-6f), fmaxf(bfhi(g.w), 1e-6f)};
;                     *(u32x4*)(Mo + row * 2048 + col) = pack8(v0, v1); } }
;         }
;     }
	v_lshlrev_b32_e32 v0, 16, v164
	v_cvt_pk_bf16_f32 v144, v144, v145
	v_cvt_pk_bf16_f32 v145, v146, v147
	v_cvt_pk_bf16_f32 v146, v150, v151
	v_cvt_pk_bf16_f32 v147, v152, v153
	global_store_dwordx4 v[148:149], v[144:147], off offset:256
	v_lshlrev_b64 v[148:149], 12, v[172:173]
	v_lshl_add_u64 v[148:149], s[16:17], 0, v[148:149]
	v_max_f32_e32 v144, 0x358637bd, v0
	v_and_b32_e32 v0, 0xffff0000, v164
	v_max_f32_e32 v145, 0x358637bd, v0
	v_lshlrev_b32_e32 v0, 16, v165
	v_max_f32_e32 v146, 0x358637bd, v0
	v_and_b32_e32 v0, 0xffff0000, v165
	v_max_f32_e32 v147, 0x358637bd, v0
	v_lshlrev_b32_e32 v0, 16, v166
	v_max_f32_e32 v150, 0x358637bd, v0
	v_and_b32_e32 v0, 0xffff0000, v166
	v_max_f32_e32 v151, 0x358637bd, v0
	v_lshlrev_b32_e32 v0, 16, v167
	v_max_f32_e32 v152, 0x358637bd, v0
	v_and_b32_e32 v0, 0xffff0000, v167
	v_max_f32_e32 v153, 0x358637bd, v0
	v_pk_mul_f32 v[146:147], v[50:51], v[146:147]
	v_pk_mul_f32 v[144:145], v[48:49], v[144:145]
	v_pk_mul_f32 v[152:153], v[46:47], v[152:153]
	v_pk_mul_f32 v[150:151], v[44:45], v[150:151]
	s_waitcnt vmcnt(6)
	v_lshlrev_b32_e32 v0, 16, v140
	v_cvt_pk_bf16_f32 v144, v144, v145
	v_cvt_pk_bf16_f32 v145, v146, v147
	v_cvt_pk_bf16_f32 v146, v150, v151
	v_cvt_pk_bf16_f32 v147, v152, v153
	v_lshl_add_u64 v[148:149], v[148:149], 0, v[160:161]
	global_store_dwordx4 v[148:149], v[144:147], off
	s_nop 1
	v_max_f32_e32 v144, 0x358637bd, v0
	v_and_b32_e32 v0, 0xffff0000, v140
	v_max_f32_e32 v145, 0x358637bd, v0
	v_lshlrev_b32_e32 v0, 16, v141
	v_max_f32_e32 v140, 0x358637bd, v0
	v_and_b32_e32 v0, 0xffff0000, v141
	v_max_f32_e32 v141, 0x358637bd, v0
	v_lshlrev_b32_e32 v0, 16, v142
	v_pk_mul_f32 v[146:147], v[18:19], v[140:141]
	v_pk_mul_f32 v[140:141], v[16:17], v[144:145]
	v_max_f32_e32 v144, 0x358637bd, v0
	v_and_b32_e32 v0, 0xffff0000, v142
	v_max_f32_e32 v145, 0x358637bd, v0
	v_lshlrev_b32_e32 v0, 16, v143
	v_max_f32_e32 v142, 0x358637bd, v0
	v_and_b32_e32 v0, 0xffff0000, v143
	v_max_f32_e32 v143, 0x358637bd, v0
	v_pk_mul_f32 v[150:151], v[14:15], v[142:143]
	v_pk_mul_f32 v[142:143], v[12:13], v[144:145]
	s_waitcnt vmcnt(6)
	v_lshlrev_b32_e32 v0, 16, v136
	v_cvt_pk_bf16_f32 v140, v140, v141
	v_cvt_pk_bf16_f32 v141, v146, v147
	v_cvt_pk_bf16_f32 v142, v142, v143
	v_cvt_pk_bf16_f32 v143, v150, v151
	global_store_dwordx4 v[148:149], v[140:143], off offset:256
	s_nop 1
	v_max_f32_e32 v140, 0x358637bd, v0
	v_and_b32_e32 v0, 0xffff0000, v136
	v_max_f32_e32 v141, 0x358637bd, v0
	v_lshlrev_b32_e32 v0, 16, v137
	v_max_f32_e32 v136, 0x358637bd, v0
	v_and_b32_e32 v0, 0xffff0000, v137
	v_max_f32_e32 v137, 0x358637bd, v0
	v_lshlrev_b32_e32 v0, 16, v138
	v_pk_mul_f32 v[142:143], v[42:43], v[136:137]
	v_pk_mul_f32 v[136:137], v[40:41], v[140:141]
	v_max_f32_e32 v140, 0x358637bd, v0
	v_and_b32_e32 v0, 0xffff0000, v138
	v_max_f32_e32 v141, 0x358637bd, v0
	v_lshlrev_b32_e32 v0, 16, v139
	v_max_f32_e32 v138, 0x358637bd, v0
	v_and_b32_e32 v0, 0xffff0000, v139
	v_max_f32_e32 v139, 0x358637bd, v0
	v_pk_mul_f32 v[144:145], v[38:39], v[138:139]
	v_pk_mul_f32 v[138:139], v[36:37], v[140:141]
	s_waitcnt vmcnt(6)
	v_lshlrev_b32_e32 v0, 16, v132
	v_cvt_pk_bf16_f32 v136, v136, v137
	v_cvt_pk_bf16_f32 v137, v142, v143
	v_cvt_pk_bf16_f32 v138, v138, v139
	v_cvt_pk_bf16_f32 v139, v144, v145
	global_store_dwordx4 v[2:3], v[136:139], off
	s_nop 1
	v_max_f32_e32 v136, 0x358637bd, v0
	v_and_b32_e32 v0, 0xffff0000, v132
	v_max_f32_e32 v137, 0x358637bd, v0
	v_lshlrev_b32_e32 v0, 16, v133
	v_max_f32_e32 v132, 0x358637bd, v0
	v_and_b32_e32 v0, 0xffff0000, v133
	v_max_f32_e32 v133, 0x358637bd, v0
	v_lshlrev_b32_e32 v0, 16, v134
	v_pk_mul_f32 v[138:139], v[10:11], v[132:133]
	v_pk_mul_f32 v[132:133], v[8:9], v[136:137]
	v_max_f32_e32 v136, 0x358637bd, v0
	v_and_b32_e32 v0, 0xffff0000, v134
	v_max_f32_e32 v137, 0x358637bd, v0
	v_lshlrev_b32_e32 v0, 16, v135
	v_max_f32_e32 v134, 0x358637bd, v0
	v_and_b32_e32 v0, 0xffff0000, v135
	v_max_f32_e32 v135, 0x358637bd, v0
	v_pk_mul_f32 v[140:141], v[6:7], v[134:135]
	v_pk_mul_f32 v[134:135], v[4:5], v[136:137]
	v_cvt_pk_bf16_f32 v132, v132, v133
	v_cvt_pk_bf16_f32 v133, v138, v139
	v_cvt_pk_bf16_f32 v134, v134, v135
	v_cvt_pk_bf16_f32 v135, v140, v141
	global_store_dwordx4 v[2:3], v[132:135], off offset:256
	s_cbranch_vccnz .LBB0_1401
	s_andn2_b64 vcc, exec, s[12:13]
	s_cbranch_vccnz .LBB0_1369
	s_barrier
	s_branch .LBB0_1369

; __device__ __forceinline__ u32x4 pack8(f32x4 v0, f32x4 v1) { u32x4 w; w.x = cvt_pk_bf16(v0[0], v0[1]); w.y = cvt_pk_bf16(v0[2], v0[3]); w.z = cvt_pk_bf16(v1[0], v1[1]); w.w = cvt_pk_bf16(v1[2], v1[3]); return w; }
;     __device__ __forceinline__ void operator()(const f32x4 (&acc)[2][2][4][2], const Unit& u, int wr, int wc, int fr, int fq) const {
;     ...
;         else { pitch = 8192; base = O0 + (size_t)(u.pm * 256) * 8192 + u.pn * 256; }
;         const int r0 = wr * 64 + fr, cl = wc * 32 + 8 * fq;
; #pragma unroll
;         for (int ai = 0; ai < 2; ++ai)
; #pragma unroll
;             for (int m = 0; m < 4; ++m) { bf16_t* rowp = base + (size_t)(r0 + ai * HALF + m * 16) * pitch + cl;
; #pragma unroll
;                 for (int bj = 0; bj < 2; ++bj) { f32x4 v0 = acc[ai][bj][m][0], v1 = acc[ai][bj][m][1];
;                     if (kind == 3) { v0 = __builtin_elementwise_max(v0, (f32x4){0.f, 0.f, 0.f, 0.f}); v1 = __builtin_elementwise_max(v1, (f32x4){0.f, 0.f, 0.f, 0.f}); v0 = v0 * v0; v1 = v1 * v1; }
;                     *(u32x4*)(rowp + bj * HALF) = pack8(v0, v1); } }
.LBB0_1696:
	s_add_u32 s4, s33, 0xffffff00
	s_addc_u32 s5, s53, -1
	s_lshl_b32 s6, s2, 8
	s_ashr_i32 s7, s6, 31
	s_lshl_b64 s[6:7], s[6:7], 14
	s_add_u32 s8, s46, s6
	s_addc_u32 s9, s47, s7
	s_lshl_b32 s6, s48, 8
	s_ashr_i32 s7, s6, 31
	s_lshl_b64 s[6:7], s[6:7], 1
	s_add_u32 s6, s8, s6
	v_max_f32_e32 v165, 0, v127
	v_max_f32_e32 v167, 0, v129
	v_max_f32_e32 v169, 0, v123
	v_max_f32_e32 v171, 0, v125
	s_addc_u32 s7, s9, s7
	v_max_f32_e32 v164, 0, v126
	v_max_f32_e32 v166, 0, v128
	v_max_f32_e32 v168, 0, v122
	v_max_f32_e32 v170, 0, v124
	v_lshl_add_u64 v[158:159], v[136:137], 1, s[6:7]
	v_pk_mul_f32 v[166:167], v[166:167], v[166:167]
	v_pk_mul_f32 v[164:165], v[164:165], v[164:165]
	v_pk_mul_f32 v[170:171], v[170:171], v[170:171]
	v_pk_mul_f32 v[168:169], v[168:169], v[168:169]
	v_lshl_add_u64 v[160:161], v[158:159], 0, v[138:139]
	v_cvt_pk_bf16_f32 v164, v164, v165
	v_cvt_pk_bf16_f32 v165, v166, v167
	v_cvt_pk_bf16_f32 v166, v168, v169
	v_cvt_pk_bf16_f32 v167, v170, v171
	global_store_dwordx4 v[160:161], v[164:167], off
	s_nop 1
	v_max_f32_e32 v165, 0, v95
	v_max_f32_e32 v167, 0, v97
	v_max_f32_e32 v169, 0, v91
	v_max_f32_e32 v171, 0, v93
	v_max_f32_e32 v164, 0, v94
	v_max_f32_e32 v166, 0, v96
	v_max_f32_e32 v168, 0, v90
	v_max_f32_e32 v170, 0, v92
	v_pk_mul_f32 v[166:167], v[166:167], v[166:167]
	v_pk_mul_f32 v[164:165], v[164:165], v[164:165]
	v_pk_mul_f32 v[170:171], v[170:171], v[170:171]
	v_pk_mul_f32 v[168:169], v[168:169], v[168:169]
	v_cvt_pk_bf16_f32 v164, v164, v165
	v_cvt_pk_bf16_f32 v165, v166, v167
	v_cvt_pk_bf16_f32 v166, v168, v169
	v_cvt_pk_bf16_f32 v167, v170, v171
	global_store_dwordx4 v[160:161], v[164:167], off offset:256
	s_nop 1
	v_max_f32_e32 v165, 0, v119
	v_max_f32_e32 v167, 0, v121
	v_max_f32_e32 v169, 0, v115
	v_max_f32_e32 v171, 0, v117
	v_max_f32_e32 v164, 0, v118
	v_max_f32_e32 v166, 0, v120
	v_max_f32_e32 v168, 0, v114
	v_max_f32_e32 v170, 0, v116
	v_pk_mul_f32 v[166:167], v[166:167], v[166:167]
	v_pk_mul_f32 v[164:165], v[164:165], v[164:165]
	v_pk_mul_f32 v[170:171], v[170:171], v[170:171]
	v_pk_mul_f32 v[168:169], v[168:169], v[168:169]
	v_lshl_add_u64 v[160:161], v[158:159], 0, v[148:149]
	v_cvt_pk_bf16_f32 v164, v164, v165
	v_cvt_pk_bf16_f32 v165, v166, v167
	v_cvt_pk_bf16_f32 v166, v168, v169
	v_cvt_pk_bf16_f32 v167, v170, v171
	global_store_dwordx4 v[160:161], v[164:167], off
	s_nop 1
	v_max_f32_e32 v165, 0, v87
	v_max_f32_e32 v167, 0, v89
	v_max_f32_e32 v169, 0, v83
	v_max_f32_e32 v171, 0, v85
	v_max_f32_e32 v164, 0, v86
	v_max_f32_e32 v166, 0, v88
	v_max_f32_e32 v168, 0, v82
	v_max_f32_e32 v170, 0, v84
	v_pk_mul_f32 v[166:167], v[166:167], v[166:167]
	v_pk_mul_f32 v[164:165], v[164:165], v[164:165]
	v_pk_mul_f32 v[170:171], v[170:171], v[170:171]
	v_pk_mul_f32 v[168:169], v[168:169], v[168:169]
	v_cvt_pk_bf16_f32 v164, v164, v165
	v_cvt_pk_bf16_f32 v165, v166, v167
	v_cvt_pk_bf16_f32 v166, v168, v169
	v_cvt_pk_bf16_f32 v167, v170, v171
	global_store_dwordx4 v[160:161], v[164:167], off offset:256
	s_nop 1
	v_max_f32_e32 v165, 0, v111
	v_max_f32_e32 v167, 0, v113
	v_max_f32_e32 v169, 0, v107
	v_max_f32_e32 v171, 0, v109
	v_max_f32_e32 v164, 0, v110
	v_max_f32_e32 v166, 0, v112
	v_max_f32_e32 v168, 0, v106
	v_max_f32_e32 v170, 0, v108
	v_pk_mul_f32 v[166:167], v[166:167], v[166:167]
	v_pk_mul_f32 v[164:165], v[164:165], v[164:165]
	v_pk_mul_f32 v[170:171], v[170:171], v[170:171]
	v_pk_mul_f32 v[168:169], v[168:169], v[168:169]
	v_lshl_add_u64 v[160:161], v[158:159], 0, v[150:151]
	v_cvt_pk_bf16_f32 v164, v164, v165
	v_cvt_pk_bf16_f32 v165, v166, v167
	v_cvt_pk_bf16_f32 v166, v168, v169
	v_cvt_pk_bf16_f32 v167, v170, v171
	global_store_dwordx4 v[160:161], v[164:167], off
	s_nop 1
	v_max_f32_e32 v165, 0, v79
	v_max_f32_e32 v167, 0, v81
	v_max_f32_e32 v169, 0, v75
	v_max_f32_e32 v171, 0, v77
	v_max_f32_e32 v164, 0, v78
	v_max_f32_e32 v166, 0, v80
	v_max_f32_e32 v168, 0, v74
	v_max_f32_e32 v170, 0, v76
	v_pk_mul_f32 v[166:167], v[166:167], v[166:167]
	v_pk_mul_f32 v[164:165], v[164:165], v[164:165]
	v_pk_mul_f32 v[170:171], v[170:171], v[170:171]
	v_pk_mul_f32 v[168:169], v[168:169], v[168:169]
	v_cvt_pk_bf16_f32 v164, v164, v165
	v_cvt_pk_bf16_f32 v165, v166, v167
	v_cvt_pk_bf16_f32 v166, v168, v169
	v_cvt_pk_bf16_f32 v167, v170, v171
	global_store_dwordx4 v[160:161], v[164:167], off offset:256
	s_nop 1
	v_max_f32_e32 v165, 0, v103
	v_max_f32_e32 v167, 0, v105
	v_max_f32_e32 v169, 0, v99
	v_max_f32_e32 v171, 0, v101
	v_max_f32_e32 v164, 0, v102
	v_max_f32_e32 v166, 0, v104
	v_max_f32_e32 v168, 0, v98
	v_max_f32_e32 v170, 0, v100
	v_pk_mul_f32 v[166:167], v[166:167], v[166:167]
	v_pk_mul_f32 v[164:165], v[164:165], v[164:165]
	v_pk_mul_f32 v[170:171], v[170:171], v[170:171]
	v_pk_mul_f32 v[168:169], v[168:169], v[168:169]
	v_lshl_add_u64 v[160:161], v[158:159], 0, v[152:153]
	v_cvt_pk_bf16_f32 v164, v164, v165
	v_cvt_pk_bf16_f32 v165, v166, v167
	v_cvt_pk_bf16_f32 v166, v168, v169
	v_cvt_pk_bf16_f32 v167, v170, v171
	global_store_dwordx4 v[160:161], v[164:167], off
	s_nop 1
	v_max_f32_e32 v165, 0, v71
	v_max_f32_e32 v167, 0, v73
	v_max_f32_e32 v169, 0, v67
	v_max_f32_e32 v171, 0, v69
	v_max_f32_e32 v164, 0, v70
	v_max_f32_e32 v166, 0, v72
	v_max_f32_e32 v168, 0, v66
	v_max_f32_e32 v170, 0, v68
	v_pk_mul_f32 v[166:167], v[166:167], v[166:167]
	v_pk_mul_f32 v[164:165], v[164:165], v[164:165]
	v_pk_mul_f32 v[170:171], v[170:171], v[170:171]
	v_pk_mul_f32 v[168:169], v[168:169], v[168:169]
	v_cvt_pk_bf16_f32 v164, v164, v165
	v_cvt_pk_bf16_f32 v165, v166, v167
	v_cvt_pk_bf16_f32 v166, v168, v169
; #define PG8_BAR __builtin_amdgcn_s_barrier()
; __device__ __forceinline__ u32x4 pack8(f32x4 v0, f32x4 v1) { u32x4 w; w.x = cvt_pk_bf16(v0[0], v0[1]); w.y = cvt_pk_bf16(v0[2], v0[3]); w.z = cvt_pk_bf16(v1[0], v1[1]); w.w = cvt_pk_bf16(v1[2], v1[3]); return w; }
; template <class Epi, class Sched, bool ALIGN_EPI = false, bool SP2 = false>
; __device__ __forceinline__ void gemm_phase(PG8_LAS unsigned char* lds, const int ldk  , const Sched& S, const Epi& E, const int wave_id) {
;     ...
;         if (!has_next) break;
; #pragma unroll
;         for (int a = 0; a < 2; ++a)
; #pragma unroll
;             for (int b = 0; b < 2; ++b)
; #pragma unroll
;                 for (int m = 0; m < 4; ++m)
; #pragma unroll
;                     for (int n = 0; n < 2; ++n) acc[a][b][m][n] = (f32x4){0.f, 0.f, 0.f, 0.f};
;         cur = nxt; cA = nA; cB = nB; ++ui; nt = S.nt(cur);
;         if constexpr (ALIGN_EPI) { if (wr == 1) PG8_BAR; }
;     __device__ __forceinline__ void operator()(const f32x4 (&acc)[2][2][4][2], const Unit& u, int wr, int wc, int fr, int fq) const {
;     ...
;             for (int m = 0; m < 4; ++m) { bf16_t* rowp = base + (size_t)(r0 + ai * HALF + m * 16) * pitch + cl;
; #pragma unroll
;                 for (int bj = 0; bj < 2; ++bj) { f32x4 v0 = acc[ai][bj][m][0], v1 = acc[ai][bj][m][1];
;                     if (kind == 3) { v0 = __builtin_elementwise_max(v0, (f32x4){0.f, 0.f, 0.f, 0.f}); v1 = __builtin_elementwise_max(v1, (f32x4){0.f, 0.f, 0.f, 0.f}); v0 = v0 * v0; v1 = v1 * v1; }
;                     *(u32x4*)(rowp + bj * HALF) = pack8(v0, v1); } }
	v_cvt_pk_bf16_f32 v167, v170, v171
	global_store_dwordx4 v[160:161], v[164:167], off offset:256
	s_nop 1
	v_max_f32_e32 v165, 0, v63
	v_max_f32_e32 v167, 0, v65
	v_max_f32_e32 v169, 0, v59
	v_max_f32_e32 v171, 0, v61
	v_max_f32_e32 v164, 0, v62
	v_max_f32_e32 v166, 0, v64
	v_max_f32_e32 v168, 0, v58
	v_max_f32_e32 v170, 0, v60
	v_pk_mul_f32 v[166:167], v[166:167], v[166:167]
	v_pk_mul_f32 v[164:165], v[164:165], v[164:165]
	v_pk_mul_f32 v[170:171], v[170:171], v[170:171]
	v_pk_mul_f32 v[168:169], v[168:169], v[168:169]
	v_lshl_add_u64 v[160:161], v[158:159], 0, v[140:141]
	v_cvt_pk_bf16_f32 v164, v164, v165
	v_cvt_pk_bf16_f32 v165, v166, v167
	v_cvt_pk_bf16_f32 v166, v168, v169
	v_cvt_pk_bf16_f32 v167, v170, v171
	global_store_dwordx4 v[160:161], v[164:167], off
	s_nop 1
	v_max_f32_e32 v165, 0, v31
	v_max_f32_e32 v167, 0, v33
	v_max_f32_e32 v169, 0, v27
	v_max_f32_e32 v171, 0, v29
	v_max_f32_e32 v164, 0, v30
	v_max_f32_e32 v166, 0, v32
	v_max_f32_e32 v168, 0, v26
	v_max_f32_e32 v170, 0, v28
	v_pk_mul_f32 v[166:167], v[166:167], v[166:167]
	v_pk_mul_f32 v[164:165], v[164:165], v[164:165]
	v_pk_mul_f32 v[170:171], v[170:171], v[170:171]
	v_pk_mul_f32 v[168:169], v[168:169], v[168:169]
	v_cvt_pk_bf16_f32 v164, v164, v165
	v_cvt_pk_bf16_f32 v165, v166, v167
	v_cvt_pk_bf16_f32 v166, v168, v169
	v_cvt_pk_bf16_f32 v167, v170, v171
	global_store_dwordx4 v[160:161], v[164:167], off offset:256
	s_nop 1
	v_max_f32_e32 v165, 0, v55
	v_max_f32_e32 v167, 0, v57
	v_max_f32_e32 v169, 0, v51
	v_max_f32_e32 v171, 0, v53
	v_max_f32_e32 v164, 0, v54
	v_max_f32_e32 v166, 0, v56
	v_max_f32_e32 v168, 0, v50
	v_max_f32_e32 v170, 0, v52
	v_pk_mul_f32 v[166:167], v[166:167], v[166:167]
	v_pk_mul_f32 v[164:165], v[164:165], v[164:165]
	v_pk_mul_f32 v[170:171], v[170:171], v[170:171]
	v_pk_mul_f32 v[168:169], v[168:169], v[168:169]
	v_lshl_add_u64 v[160:161], v[158:159], 0, v[142:143]
	v_cvt_pk_bf16_f32 v164, v164, v165
	v_cvt_pk_bf16_f32 v165, v166, v167
	v_cvt_pk_bf16_f32 v166, v168, v169
	v_cvt_pk_bf16_f32 v167, v170, v171
	global_store_dwordx4 v[160:161], v[164:167], off
	s_nop 1
	v_max_f32_e32 v165, 0, v23
	v_max_f32_e32 v167, 0, v25
	v_max_f32_e32 v169, 0, v19
	v_max_f32_e32 v171, 0, v21
	v_max_f32_e32 v164, 0, v22
	v_max_f32_e32 v166, 0, v24
	v_max_f32_e32 v168, 0, v18
	v_max_f32_e32 v170, 0, v20
	v_pk_mul_f32 v[166:167], v[166:167], v[166:167]
	v_pk_mul_f32 v[164:165], v[164:165], v[164:165]
	v_pk_mul_f32 v[170:171], v[170:171], v[170:171]
	v_pk_mul_f32 v[168:169], v[168:169], v[168:169]
	v_cvt_pk_bf16_f32 v164, v164, v165
	v_cvt_pk_bf16_f32 v165, v166, v167
	v_cvt_pk_bf16_f32 v166, v168, v169
	v_cvt_pk_bf16_f32 v167, v170, v171
	global_store_dwordx4 v[160:161], v[164:167], off offset:256
	s_nop 1
	v_max_f32_e32 v165, 0, v47
	v_max_f32_e32 v167, 0, v49
	v_max_f32_e32 v169, 0, v43
	v_max_f32_e32 v171, 0, v45
	v_max_f32_e32 v164, 0, v46
	v_max_f32_e32 v166, 0, v48
	v_max_f32_e32 v168, 0, v42
	v_max_f32_e32 v170, 0, v44
	v_pk_mul_f32 v[166:167], v[166:167], v[166:167]
	v_pk_mul_f32 v[164:165], v[164:165], v[164:165]
	v_pk_mul_f32 v[170:171], v[170:171], v[170:171]
	v_pk_mul_f32 v[168:169], v[168:169], v[168:169]
	v_lshl_add_u64 v[160:161], v[158:159], 0, v[144:145]
	v_cvt_pk_bf16_f32 v164, v164, v165
	v_cvt_pk_bf16_f32 v165, v166, v167
	v_cvt_pk_bf16_f32 v166, v168, v169
	v_cvt_pk_bf16_f32 v167, v170, v171
	global_store_dwordx4 v[160:161], v[164:167], off
	s_nop 1
	v_max_f32_e32 v165, 0, v15
	v_max_f32_e32 v167, 0, v17
	v_max_f32_e32 v169, 0, v11
	v_max_f32_e32 v171, 0, v13
	v_max_f32_e32 v164, 0, v14
	v_max_f32_e32 v166, 0, v16
	v_max_f32_e32 v168, 0, v10
	v_max_f32_e32 v170, 0, v12
	v_pk_mul_f32 v[166:167], v[166:167], v[166:167]
	v_pk_mul_f32 v[164:165], v[164:165], v[164:165]
	v_pk_mul_f32 v[170:171], v[170:171], v[170:171]
	v_pk_mul_f32 v[168:169], v[168:169], v[168:169]
	v_cvt_pk_bf16_f32 v164, v164, v165
	v_cvt_pk_bf16_f32 v165, v166, v167
	v_cvt_pk_bf16_f32 v166, v168, v169
	v_cvt_pk_bf16_f32 v167, v170, v171
	global_store_dwordx4 v[160:161], v[164:167], off offset:256
	s_nop 1
	v_lshl_add_u64 v[164:165], v[158:159], 0, v[146:147]
	v_max_f32_e32 v159, 0, v39
	v_max_f32_e32 v161, 0, v41
	v_max_f32_e32 v167, 0, v35
	v_max_f32_e32 v169, 0, v37
	v_max_f32_e32 v158, 0, v38
	v_max_f32_e32 v160, 0, v40
	v_max_f32_e32 v166, 0, v34
	v_max_f32_e32 v168, 0, v36
	v_pk_mul_f32 v[160:161], v[160:161], v[160:161]
	v_pk_mul_f32 v[158:159], v[158:159], v[158:159]
	v_pk_mul_f32 v[168:169], v[168:169], v[168:169]
	v_pk_mul_f32 v[166:167], v[166:167], v[166:167]
	v_cvt_pk_bf16_f32 v158, v158, v159
	v_cvt_pk_bf16_f32 v159, v160, v161
	v_cvt_pk_bf16_f32 v160, v166, v167
	v_cvt_pk_bf16_f32 v161, v168, v169
	global_store_dwordx4 v[164:165], v[158:161], off
	s_nop 1
	v_max_f32_e32 v159, 0, v7
	v_max_f32_e32 v161, 0, v9
	v_max_f32_e32 v167, 0, v3
	v_max_f32_e32 v169, 0, v5
	v_max_f32_e32 v158, 0, v6
	v_max_f32_e32 v160, 0, v8
	v_max_f32_e32 v166, 0, v2
	v_max_f32_e32 v168, 0, v4
	v_pk_mul_f32 v[160:161], v[160:161], v[160:161]
	v_pk_mul_f32 v[158:159], v[158:159], v[158:159]
	v_pk_mul_f32 v[168:169], v[168:169], v[168:169]
	v_pk_mul_f32 v[166:167], v[166:167], v[166:167]
	v_cvt_pk_bf16_f32 v158, v158, v159
	v_cvt_pk_bf16_f32 v159, v160, v161
	v_cvt_pk_bf16_f32 v160, v166, v167
	v_cvt_pk_bf16_f32 v161, v168, v169
	s_andn2_b64 vcc, exec, s[34:35]
	global_store_dwordx4 v[164:165], v[158:161], off offset:256
	s_cbranch_vccnz .LBB0_1699
	s_andn2_b64 vcc, exec, s[10:11]
	s_mov_b32 s35, s61
	s_cbranch_vccnz .LBB0_1689
	s_barrier
	s_branch .LBB0_1689
